# attention QK^T second half: K-fragment LDS reads pipelined 3-deep (two extra register quads made by parking four idle registers) instead of read->wait(0)->MFMA through one quad
# speedup vs baseline: 1.0092x; 1.0019x over previous
; #define LAS __attribute__((address_space(3)))
; __device__ __forceinline__ int opaque_tid() { int t = threadIdx.x; asm volatile("" : "+v"(t)); return t; }
; __device__ void attn_item(const bf16_t* __restrict__ QX, const bf16_t* __restrict__ KV, bf16_t* __restrict__ O, int tt, int head, LAS unsigned char* lds) {
;   const int tid = opaque_tid(), w = tid >> 6, l = tid & 63; const int row0 = tt * 256; const int b = tt < 64 ? (tt >> 3) : 8; const int mrow0 = b * 256;
;   constexpr unsigned KS = 528, VS = 576;
; #pragma unroll 4
;   for (int it = 0; it < 16; ++it) { const int q = tid + it * 512, m = q >> 5, c = q & 31;
;     *(LAS u32x4*)(lds + m * KS + c * 16) = *(const u32x4*)(KV + (size_t)(mrow0 + m) * 2048 + head * 256 + c * 8); }
;   __syncthreads();
;   const int il = l & 31, h = l >> 5, i16 = l & 15, q4 = i16 >> 2, p4 = i16 & 3, G1 = (l >> 4) & 1;
;   const int row = row0 + w * 32 + il;
;   bf16x8 pf[8][2];
;   float mxp = -3.0e38f, sum = 0.f;
;   const bf16_t* qp = QX + (size_t)row * 1024 + head * 256 + 8 * h;
; #pragma unroll
;   for (int hf = 0; hf < 2; ++hf) {
;     f32x16 sc[4];
; #pragma unroll
;     for (int i = 0; i < 4; ++i) sc[i] = (f32x16){};
.LBB0_982:
	v_readlane_b32 s20, v255, 62
	v_readlane_b32 s12, v255, 61
	s_min_i32 s7, s20, 64
	s_lshl_b32 s22, s12, 8
	s_lshl_b32 s7, s7, 5
	s_ashr_i32 s23, s22, 31
	v_mov_b32_e32 v133, v214
	s_and_b32 s7, s7, 0xffffff00
	s_lshl_b64 s[34:35], s[22:23], 1
	s_add_u32 s12, s14, s34
	v_and_b32_e32 v0, 31, v133
	s_addc_u32 s13, s15, s35
	v_lshlrev_b32_e32 v160, 4, v0
	v_lshl_add_u64 v[128:129], s[12:13], 0, v[160:161]
	v_add_u32_e32 v132, 0, v160
	v_lshrrev_b32_e32 v1, 5, v133
	v_add_u32_e32 v2, s7, v1
	v_ashrrev_i32_e32 v3, 31, v2
	v_lshlrev_b64 v[2:3], 12, v[2:3]
	v_lshl_add_u64 v[2:3], v[128:129], 0, v[2:3]
	v_mad_u32_u24 v6, v1, s59, v132
	s_mov_b64 s[36:37], 0x10000
	v_add_u32_e32 v7, 0x10800, v6
	global_load_dwordx4 v[8:11], v[2:3], off
	v_lshl_add_u64 v[2:3], v[2:3], 0, s[36:37]
	global_load_dwordx4 v[12:15], v[2:3], off
	v_lshl_add_u64 v[2:3], v[2:3], 0, s[36:37]
	global_load_dwordx4 v[16:19], v[2:3], off
	v_lshl_add_u64 v[2:3], v[2:3], 0, s[36:37]
	global_load_dwordx4 v[20:23], v[2:3], off
	v_lshl_add_u64 v[2:3], v[2:3], 0, s[36:37]
	global_load_dwordx4 v[24:27], v[2:3], off
	v_lshl_add_u64 v[2:3], v[2:3], 0, s[36:37]
	global_load_dwordx4 v[28:31], v[2:3], off
	v_lshl_add_u64 v[2:3], v[2:3], 0, s[36:37]
	global_load_dwordx4 v[32:35], v[2:3], off
	v_lshl_add_u64 v[2:3], v[2:3], 0, s[36:37]
	global_load_dwordx4 v[36:39], v[2:3], off
	v_lshl_add_u64 v[2:3], v[2:3], 0, s[36:37]
	global_load_dwordx4 v[40:43], v[2:3], off
	v_lshl_add_u64 v[2:3], v[2:3], 0, s[36:37]
	global_load_dwordx4 v[44:47], v[2:3], off
	v_lshl_add_u64 v[2:3], v[2:3], 0, s[36:37]
	global_load_dwordx4 v[48:51], v[2:3], off
	v_lshl_add_u64 v[2:3], v[2:3], 0, s[36:37]
	global_load_dwordx4 v[52:55], v[2:3], off
	v_lshl_add_u64 v[2:3], v[2:3], 0, s[36:37]
	global_load_dwordx4 v[56:59], v[2:3], off
	v_lshl_add_u64 v[2:3], v[2:3], 0, s[36:37]
	global_load_dwordx4 v[60:63], v[2:3], off
	v_lshl_add_u64 v[2:3], v[2:3], 0, s[36:37]
	global_load_dwordx4 v[64:67], v[2:3], off
	v_lshl_add_u64 v[2:3], v[2:3], 0, s[36:37]
	global_load_dwordx4 v[68:71], v[2:3], off
	s_waitcnt vmcnt(15)
	ds_write_b128 v6, v[8:11]
	s_waitcnt vmcnt(14)
	ds_write_b128 v6, v[12:15] offset:8448
	s_waitcnt vmcnt(13)
	ds_write_b128 v6, v[16:19] offset:16896
	s_waitcnt vmcnt(12)
	ds_write_b128 v6, v[20:23] offset:25344
	s_waitcnt vmcnt(11)
	ds_write_b128 v6, v[24:27] offset:33792
	s_waitcnt vmcnt(10)
	ds_write_b128 v6, v[28:31] offset:42240
	s_waitcnt vmcnt(9)
	ds_write_b128 v6, v[32:35] offset:50688
	s_waitcnt vmcnt(8)
	ds_write_b128 v6, v[36:39] offset:59136
	s_waitcnt vmcnt(7)
	ds_write_b128 v7, v[40:43]
	s_waitcnt vmcnt(6)
	ds_write_b128 v7, v[44:47] offset:8448
	s_waitcnt vmcnt(5)
	ds_write_b128 v7, v[48:51] offset:16896
	s_waitcnt vmcnt(4)
	ds_write_b128 v7, v[52:55] offset:25344
	s_waitcnt vmcnt(3)
	ds_write_b128 v7, v[56:59] offset:33792
	s_waitcnt vmcnt(2)
	ds_write_b128 v7, v[60:63] offset:42240
	s_waitcnt vmcnt(1)
	ds_write_b128 v7, v[64:67] offset:50688
	s_waitcnt vmcnt(0)
	ds_write_b128 v7, v[68:71] offset:59136
	s_movk_i32 s12, 0x2000
	v_ashrrev_i32_e32 v1, 1, v133
	v_and_b32_e32 v1, 0xffffffe0, v1
	v_lshl_add_u32 v1, s20, 8, v1
	v_or_b32_e32 v130, v1, v0
	v_bfe_u32 v136, v133, 5, 1
	v_ashrrev_i32_e32 v131, 31, v130
	v_readlane_b32 s12, v255, 44
	v_mul_u32_u24_e32 v2, 0x210, v0
	v_lshlrev_b32_e32 v160, 4, v136
	v_lshlrev_b64 v[0:1], 11, v[130:131]
	s_add_u32 s12, s12, s34
	v_readlane_b32 s13, v255, 45
	v_or_b32_e32 v0, v0, v160
	s_addc_u32 s13, s13, s35
	v_lshl_add_u64 v[134:135], s[12:13], 0, v[0:1]
	v_mov_b32_e32 v0, 0
	v_add3_u32 v138, v2, v160, 0
	s_mov_b32 s12, 0
	v_mov_b64_e32 v[64:65], v[134:135]
	v_mov_b32_e32 v1, v0
	v_mov_b32_e32 v2, v0
	v_mov_b32_e32 v3, v0
	v_mov_b32_e32 v4, v0
	v_mov_b32_e32 v5, v0
	v_mov_b32_e32 v6, v0
	v_mov_b32_e32 v7, v0
	v_mov_b32_e32 v8, v0
	v_mov_b32_e32 v9, v0
	v_mov_b32_e32 v10, v0
	v_mov_b32_e32 v11, v0
	v_mov_b32_e32 v12, v0
	v_mov_b32_e32 v13, v0
	v_mov_b32_e32 v14, v0
	v_mov_b32_e32 v15, v0
	v_mov_b32_e32 v16, v0
	v_mov_b32_e32 v17, v0
	v_mov_b32_e32 v18, v0
	v_mov_b32_e32 v19, v0
	v_mov_b32_e32 v20, v0
	v_mov_b32_e32 v21, v0
	v_mov_b32_e32 v22, v0
	v_mov_b32_e32 v23, v0
	v_mov_b32_e32 v24, v0
	v_mov_b32_e32 v25, v0
	v_mov_b32_e32 v26, v0
	v_mov_b32_e32 v27, v0
	v_mov_b32_e32 v28, v0
	v_mov_b32_e32 v29, v0
	v_mov_b32_e32 v30, v0
	v_mov_b32_e32 v31, v0
	v_mov_b32_e32 v32, v0
	v_mov_b32_e32 v33, v0
	v_mov_b32_e32 v34, v0
	v_mov_b32_e32 v35, v0
	v_mov_b32_e32 v36, v0
	v_mov_b32_e32 v37, v0
	v_mov_b32_e32 v38, v0
	v_mov_b32_e32 v39, v0
	v_mov_b32_e32 v40, v0
	v_mov_b32_e32 v41, v0
	v_mov_b32_e32 v42, v0
	v_mov_b32_e32 v43, v0
	v_mov_b32_e32 v44, v0
	v_mov_b32_e32 v45, v0
	v_mov_b32_e32 v46, v0
	v_mov_b32_e32 v47, v0
	v_mov_b32_e32 v48, v0
	v_mov_b32_e32 v49, v0
	v_mov_b32_e32 v50, v0
	v_mov_b32_e32 v51, v0
	v_mov_b32_e32 v52, v0
	v_mov_b32_e32 v53, v0
	v_mov_b32_e32 v54, v0
	v_mov_b32_e32 v55, v0
	v_mov_b32_e32 v56, v0
	v_mov_b32_e32 v57, v0
	v_mov_b32_e32 v58, v0
	v_mov_b32_e32 v59, v0
	v_mov_b32_e32 v60, v0
	v_mov_b32_e32 v61, v0
	v_mov_b32_e32 v62, v0
	v_mov_b32_e32 v63, v0
	s_waitcnt lgkmcnt(0)
	s_barrier
; #define LAS __attribute__((address_space(3)))
; __device__ __forceinline__ f32x16 mfma32(bf16x8 a, bf16x8 b, f32x16 c) { return __builtin_amdgcn_mfma_f32_32x32x16_bf16(a, b, c, 0, 0, 0); }
; __device__ void attn_item(const bf16_t* __restrict__ QX, const bf16_t* __restrict__ KV, bf16_t* __restrict__ O, int tt, int head, LAS unsigned char* lds) {
;     ...
; #pragma unroll 4
;     for (int ks = 0; ks < 16; ++ks) {
;       const bf16x8 B = *(const bf16x8*)(qp + 16 * ks);
; #pragma unroll
;       for (int mt = 0; mt < 4; ++mt) sc[mt] = mfma32(*(const LAS bf16x8*)(lds + ((hf * 4 + mt) * 32 + il) * KS + (16 * ks + 8 * h) * 2), B, sc[mt]);
;     }
	global_load_dwordx4 v[150:153], v[64:65], off offset:-64
	global_load_dwordx4 v[154:157], v[64:65], off offset:-32
	global_load_dwordx4 v[174:177], v[64:65], off
	global_load_dwordx4 v[178:181], v[64:65], off offset:32
	global_load_dwordx4 v[182:185], v[64:65], off offset:64
	global_load_dwordx4 v[186:189], v[64:65], off offset:96
	global_load_dwordx4 v[190:193], v[64:65], off offset:128
	global_load_dwordx4 v[194:197], v[64:65], off offset:160
	global_load_dwordx4 v[198:201], v[64:65], off offset:192
	global_load_dwordx4 v[202:205], v[64:65], off offset:224
	global_load_dwordx4 v[206:209], v[64:65], off offset:256
	global_load_dwordx4 v[226:229], v[64:65], off offset:288
	global_load_dwordx4 v[232:235], v[64:65], off offset:320
	global_load_dwordx4 v[236:239], v[64:65], off offset:352
	global_load_dwordx4 v[240:243], v[64:65], off offset:384
	global_load_dwordx4 v[66:69], v[64:65], off offset:416
	ds_read_b128 v[70:73], v138 offset:0
	ds_read_b128 v[74:77], v138 offset:16896
	ds_read_b128 v[78:81], v138 offset:33792
	ds_read_b128 v[82:85], v138 offset:50688
	s_waitcnt vmcnt(15)
	s_waitcnt lgkmcnt(3)
	v_mfma_f32_32x32x16_bf16 v[48:63], v[70:73], v[150:153], v[48:63]
	ds_read_b128 v[70:73], v138 offset:32
	s_waitcnt lgkmcnt(3)
	v_mfma_f32_32x32x16_bf16 v[32:47], v[74:77], v[150:153], v[32:47]
	ds_read_b128 v[74:77], v138 offset:16928
	s_waitcnt lgkmcnt(3)
	v_mfma_f32_32x32x16_bf16 v[16:31], v[78:81], v[150:153], v[16:31]
	ds_read_b128 v[78:81], v138 offset:33824
	s_waitcnt lgkmcnt(3)
	v_mfma_f32_32x32x16_bf16 v[0:15], v[82:85], v[150:153], v[0:15]
	ds_read_b128 v[82:85], v138 offset:50720
	s_waitcnt vmcnt(14)
	s_waitcnt lgkmcnt(3)
	v_mfma_f32_32x32x16_bf16 v[48:63], v[70:73], v[154:157], v[48:63]
	ds_read_b128 v[70:73], v138 offset:64
	s_waitcnt lgkmcnt(3)
	v_mfma_f32_32x32x16_bf16 v[32:47], v[74:77], v[154:157], v[32:47]
	ds_read_b128 v[74:77], v138 offset:16960
	s_waitcnt lgkmcnt(3)
	v_mfma_f32_32x32x16_bf16 v[16:31], v[78:81], v[154:157], v[16:31]
	ds_read_b128 v[78:81], v138 offset:33856
	s_waitcnt lgkmcnt(3)
	v_mfma_f32_32x32x16_bf16 v[0:15], v[82:85], v[154:157], v[0:15]
	ds_read_b128 v[82:85], v138 offset:50752
	s_waitcnt vmcnt(13)
	s_waitcnt lgkmcnt(3)
	v_mfma_f32_32x32x16_bf16 v[48:63], v[70:73], v[174:177], v[48:63]
	ds_read_b128 v[70:73], v138 offset:96
	s_waitcnt lgkmcnt(3)
	v_mfma_f32_32x32x16_bf16 v[32:47], v[74:77], v[174:177], v[32:47]
	ds_read_b128 v[74:77], v138 offset:16992
	s_waitcnt lgkmcnt(3)
	v_mfma_f32_32x32x16_bf16 v[16:31], v[78:81], v[174:177], v[16:31]
	ds_read_b128 v[78:81], v138 offset:33888
	s_waitcnt lgkmcnt(3)
	v_mfma_f32_32x32x16_bf16 v[0:15], v[82:85], v[174:177], v[0:15]
	ds_read_b128 v[82:85], v138 offset:50784
	s_waitcnt vmcnt(12)
	s_waitcnt lgkmcnt(3)
	v_mfma_f32_32x32x16_bf16 v[48:63], v[70:73], v[178:181], v[48:63]
	ds_read_b128 v[70:73], v138 offset:128
	s_waitcnt lgkmcnt(3)
	v_mfma_f32_32x32x16_bf16 v[32:47], v[74:77], v[178:181], v[32:47]
	ds_read_b128 v[74:77], v138 offset:17024
	s_waitcnt lgkmcnt(3)
	v_mfma_f32_32x32x16_bf16 v[16:31], v[78:81], v[178:181], v[16:31]
	ds_read_b128 v[78:81], v138 offset:33920
	s_waitcnt lgkmcnt(3)
	v_mfma_f32_32x32x16_bf16 v[0:15], v[82:85], v[178:181], v[0:15]
	ds_read_b128 v[82:85], v138 offset:50816
	s_waitcnt vmcnt(11)
	s_waitcnt lgkmcnt(3)
	v_mfma_f32_32x32x16_bf16 v[48:63], v[70:73], v[182:185], v[48:63]
	ds_read_b128 v[70:73], v138 offset:160
	s_waitcnt lgkmcnt(3)
	v_mfma_f32_32x32x16_bf16 v[32:47], v[74:77], v[182:185], v[32:47]
	ds_read_b128 v[74:77], v138 offset:17056
	s_waitcnt lgkmcnt(3)
	v_mfma_f32_32x32x16_bf16 v[16:31], v[78:81], v[182:185], v[16:31]
	ds_read_b128 v[78:81], v138 offset:33952
	s_waitcnt lgkmcnt(3)
	v_mfma_f32_32x32x16_bf16 v[0:15], v[82:85], v[182:185], v[0:15]
	ds_read_b128 v[82:85], v138 offset:50848
	s_waitcnt vmcnt(10)
	s_waitcnt lgkmcnt(3)
	v_mfma_f32_32x32x16_bf16 v[48:63], v[70:73], v[186:189], v[48:63]
	ds_read_b128 v[70:73], v138 offset:192
	s_waitcnt lgkmcnt(3)
	v_mfma_f32_32x32x16_bf16 v[32:47], v[74:77], v[186:189], v[32:47]
	ds_read_b128 v[74:77], v138 offset:17088
	s_waitcnt lgkmcnt(3)
	v_mfma_f32_32x32x16_bf16 v[16:31], v[78:81], v[186:189], v[16:31]
	ds_read_b128 v[78:81], v138 offset:33984
	s_waitcnt lgkmcnt(3)
	v_mfma_f32_32x32x16_bf16 v[0:15], v[82:85], v[186:189], v[0:15]
	ds_read_b128 v[82:85], v138 offset:50880
	s_waitcnt vmcnt(9)
	s_waitcnt lgkmcnt(3)
	v_mfma_f32_32x32x16_bf16 v[48:63], v[70:73], v[190:193], v[48:63]
	ds_read_b128 v[70:73], v138 offset:224
	s_waitcnt lgkmcnt(3)
	v_mfma_f32_32x32x16_bf16 v[32:47], v[74:77], v[190:193], v[32:47]
	ds_read_b128 v[74:77], v138 offset:17120
	s_waitcnt lgkmcnt(3)
	v_mfma_f32_32x32x16_bf16 v[16:31], v[78:81], v[190:193], v[16:31]
	ds_read_b128 v[78:81], v138 offset:34016
	s_waitcnt lgkmcnt(3)
	v_mfma_f32_32x32x16_bf16 v[0:15], v[82:85], v[190:193], v[0:15]
	ds_read_b128 v[82:85], v138 offset:50912
	s_waitcnt vmcnt(8)
	s_waitcnt lgkmcnt(3)
	v_mfma_f32_32x32x16_bf16 v[48:63], v[70:73], v[194:197], v[48:63]
	ds_read_b128 v[70:73], v138 offset:256
	s_waitcnt lgkmcnt(3)
	v_mfma_f32_32x32x16_bf16 v[32:47], v[74:77], v[194:197], v[32:47]
	ds_read_b128 v[74:77], v138 offset:17152
	s_waitcnt lgkmcnt(3)
	v_mfma_f32_32x32x16_bf16 v[16:31], v[78:81], v[194:197], v[16:31]
	ds_read_b128 v[78:81], v138 offset:34048
	s_waitcnt lgkmcnt(3)
	v_mfma_f32_32x32x16_bf16 v[0:15], v[82:85], v[194:197], v[0:15]
	ds_read_b128 v[82:85], v138 offset:50944
	s_waitcnt vmcnt(7)
	s_waitcnt lgkmcnt(3)
	v_mfma_f32_32x32x16_bf16 v[48:63], v[70:73], v[198:201], v[48:63]
	ds_read_b128 v[70:73], v138 offset:288
	s_waitcnt lgkmcnt(3)
	v_mfma_f32_32x32x16_bf16 v[32:47], v[74:77], v[198:201], v[32:47]
	ds_read_b128 v[74:77], v138 offset:17184
	s_waitcnt lgkmcnt(3)
; #define LAS __attribute__((address_space(3)))
; __device__ __forceinline__ f32x16 mfma32(bf16x8 a, bf16x8 b, f32x16 c) { return __builtin_amdgcn_mfma_f32_32x32x16_bf16(a, b, c, 0, 0, 0); }
; __device__ void attn_item(const bf16_t* __restrict__ QX, const bf16_t* __restrict__ KV, bf16_t* __restrict__ O, int tt, int head, LAS unsigned char* lds) {
;     ...
;     for (int i = 0; i < 4; ++i) sc[i] = (f32x16){};
; #pragma unroll 4
;     for (int ks = 0; ks < 16; ++ks) {
;       const bf16x8 B = *(const bf16x8*)(qp + 16 * ks);
; #pragma unroll
;       for (int mt = 0; mt < 4; ++mt) sc[mt] = mfma32(*(const LAS bf16x8*)(lds + ((hf * 4 + mt) * 32 + il) * KS + (16 * ks + 8 * h) * 2), B, sc[mt]);
;     ...
;     float mx = mxp;
; #pragma unroll
;     for (int mt = 0; mt < 4; ++mt)
; #pragma unroll
;       for (int r = 0; r < 16; ++r) mx = fmaxf(mx, sc[mt][r]);
;     mx = fmaxf(mx, __shfl_xor(mx, 32));
	v_mfma_f32_32x32x16_bf16 v[16:31], v[78:81], v[198:201], v[16:31]
	ds_read_b128 v[78:81], v138 offset:34080
	s_waitcnt lgkmcnt(3)
	v_mfma_f32_32x32x16_bf16 v[0:15], v[82:85], v[198:201], v[0:15]
	ds_read_b128 v[82:85], v138 offset:50976
	s_waitcnt vmcnt(6)
	s_waitcnt lgkmcnt(3)
	v_mfma_f32_32x32x16_bf16 v[48:63], v[70:73], v[202:205], v[48:63]
	ds_read_b128 v[70:73], v138 offset:320
	s_waitcnt lgkmcnt(3)
	v_mfma_f32_32x32x16_bf16 v[32:47], v[74:77], v[202:205], v[32:47]
	ds_read_b128 v[74:77], v138 offset:17216
	s_waitcnt lgkmcnt(3)
	v_mfma_f32_32x32x16_bf16 v[16:31], v[78:81], v[202:205], v[16:31]
	ds_read_b128 v[78:81], v138 offset:34112
	s_waitcnt lgkmcnt(3)
	v_mfma_f32_32x32x16_bf16 v[0:15], v[82:85], v[202:205], v[0:15]
	ds_read_b128 v[82:85], v138 offset:51008
	s_waitcnt vmcnt(5)
	s_waitcnt lgkmcnt(3)
	v_mfma_f32_32x32x16_bf16 v[48:63], v[70:73], v[206:209], v[48:63]
	ds_read_b128 v[70:73], v138 offset:352
	s_waitcnt lgkmcnt(3)
	v_mfma_f32_32x32x16_bf16 v[32:47], v[74:77], v[206:209], v[32:47]
	ds_read_b128 v[74:77], v138 offset:17248
	s_waitcnt lgkmcnt(3)
	v_mfma_f32_32x32x16_bf16 v[16:31], v[78:81], v[206:209], v[16:31]
	ds_read_b128 v[78:81], v138 offset:34144
	s_waitcnt lgkmcnt(3)
	v_mfma_f32_32x32x16_bf16 v[0:15], v[82:85], v[206:209], v[0:15]
	ds_read_b128 v[82:85], v138 offset:51040
	s_waitcnt vmcnt(4)
	s_waitcnt lgkmcnt(3)
	v_mfma_f32_32x32x16_bf16 v[48:63], v[70:73], v[226:229], v[48:63]
	ds_read_b128 v[70:73], v138 offset:384
	s_waitcnt lgkmcnt(3)
	v_mfma_f32_32x32x16_bf16 v[32:47], v[74:77], v[226:229], v[32:47]
	ds_read_b128 v[74:77], v138 offset:17280
	s_waitcnt lgkmcnt(3)
	v_mfma_f32_32x32x16_bf16 v[16:31], v[78:81], v[226:229], v[16:31]
	ds_read_b128 v[78:81], v138 offset:34176
	s_waitcnt lgkmcnt(3)
	v_mfma_f32_32x32x16_bf16 v[0:15], v[82:85], v[226:229], v[0:15]
	ds_read_b128 v[82:85], v138 offset:51072
	s_waitcnt vmcnt(3)
	s_waitcnt lgkmcnt(3)
	v_mfma_f32_32x32x16_bf16 v[48:63], v[70:73], v[232:235], v[48:63]
	ds_read_b128 v[70:73], v138 offset:416
	s_waitcnt lgkmcnt(3)
	v_mfma_f32_32x32x16_bf16 v[32:47], v[74:77], v[232:235], v[32:47]
	ds_read_b128 v[74:77], v138 offset:17312
	s_waitcnt lgkmcnt(3)
	v_mfma_f32_32x32x16_bf16 v[16:31], v[78:81], v[232:235], v[16:31]
	ds_read_b128 v[78:81], v138 offset:34208
	s_waitcnt lgkmcnt(3)
	v_mfma_f32_32x32x16_bf16 v[0:15], v[82:85], v[232:235], v[0:15]
	ds_read_b128 v[82:85], v138 offset:51104
	s_waitcnt vmcnt(2)
	s_waitcnt lgkmcnt(3)
	v_mfma_f32_32x32x16_bf16 v[48:63], v[70:73], v[236:239], v[48:63]
	ds_read_b128 v[70:73], v138 offset:448
	s_waitcnt lgkmcnt(3)
	v_mfma_f32_32x32x16_bf16 v[32:47], v[74:77], v[236:239], v[32:47]
	ds_read_b128 v[74:77], v138 offset:17344
	s_waitcnt lgkmcnt(3)
	v_mfma_f32_32x32x16_bf16 v[16:31], v[78:81], v[236:239], v[16:31]
	ds_read_b128 v[78:81], v138 offset:34240
	s_waitcnt lgkmcnt(3)
	v_mfma_f32_32x32x16_bf16 v[0:15], v[82:85], v[236:239], v[0:15]
	ds_read_b128 v[82:85], v138 offset:51136
	s_waitcnt vmcnt(1)
	s_waitcnt lgkmcnt(3)
	v_mfma_f32_32x32x16_bf16 v[48:63], v[70:73], v[240:243], v[48:63]
	ds_read_b128 v[70:73], v138 offset:480
	s_waitcnt lgkmcnt(3)
	v_mfma_f32_32x32x16_bf16 v[32:47], v[74:77], v[240:243], v[32:47]
	ds_read_b128 v[74:77], v138 offset:17376
	s_waitcnt lgkmcnt(3)
	v_mfma_f32_32x32x16_bf16 v[16:31], v[78:81], v[240:243], v[16:31]
	ds_read_b128 v[78:81], v138 offset:34272
	s_waitcnt lgkmcnt(3)
	v_mfma_f32_32x32x16_bf16 v[0:15], v[82:85], v[240:243], v[0:15]
	ds_read_b128 v[82:85], v138 offset:51168
	s_waitcnt vmcnt(0)
	s_waitcnt lgkmcnt(3)
	v_mfma_f32_32x32x16_bf16 v[48:63], v[70:73], v[66:69], v[48:63]
	s_waitcnt lgkmcnt(2)
	v_mfma_f32_32x32x16_bf16 v[32:47], v[74:77], v[66:69], v[32:47]
	s_waitcnt lgkmcnt(1)
	v_mfma_f32_32x32x16_bf16 v[16:31], v[78:81], v[66:69], v[16:31]
	s_waitcnt lgkmcnt(0)
	v_mfma_f32_32x32x16_bf16 v[0:15], v[82:85], v[66:69], v[0:15]
	s_movk_i32 s12, 0x200
	v_and_b32_e32 v65, 64, v219
	v_xor_b32_e32 v64, 32, v219
	v_add_u32_e32 v65, 64, v65
	v_cmp_lt_i32_e32 vcc, v64, v65
	s_mov_b32 s13, 0xff61b1e6
	s_mov_b32 s12, 0
	v_cndmask_b32_e32 v64, v219, v64, vcc
	v_lshlrev_b32_e32 v137, 2, v64
	v_max3_f32 v64, v48, s13, v49
	v_max3_f32 v64, v64, v50, v51
	v_max3_f32 v64, v64, v52, v53
	v_max3_f32 v64, v64, v54, v55
	v_max3_f32 v64, v64, v56, v57
	v_max3_f32 v64, v64, v58, v59
	v_max3_f32 v64, v64, v60, v61
	v_max3_f32 v64, v64, v62, v63
	v_max3_f32 v64, v64, v32, v33
	v_max3_f32 v64, v64, v34, v35
	v_max3_f32 v64, v64, v36, v37
	v_max3_f32 v64, v64, v38, v39
	v_max3_f32 v64, v64, v40, v41
	v_max3_f32 v64, v64, v42, v43
	v_max3_f32 v64, v64, v44, v45
	v_max3_f32 v64, v64, v46, v47
	v_max3_f32 v64, v64, v16, v17
	v_max3_f32 v64, v64, v18, v19
	v_max3_f32 v64, v64, v20, v21
	v_max3_f32 v64, v64, v22, v23
	v_max3_f32 v64, v64, v24, v25
	v_max3_f32 v64, v64, v26, v27
	v_max3_f32 v64, v64, v28, v29
	v_max3_f32 v64, v64, v30, v31
	v_max3_f32 v64, v64, v0, v1
	v_max3_f32 v64, v64, v2, v3
	v_max3_f32 v64, v64, v4, v5
	v_max3_f32 v64, v64, v6, v7
	v_max3_f32 v64, v64, v8, v9
	v_max3_f32 v64, v64, v10, v11
	v_max3_f32 v64, v64, v12, v13
	v_max3_f32 v139, v64, v14, v15
	ds_bpermute_b32 v140, v137, v139
	v_mov_b32_e32 v64, 0
	v_mov_b32_e32 v65, v64
	v_mov_b32_e32 v66, v64
	v_mov_b32_e32 v67, v64
	v_mov_b32_e32 v68, v64
	v_mov_b32_e32 v69, v64
	v_mov_b32_e32 v70, v64
	v_mov_b32_e32 v71, v64
	v_mov_b32_e32 v72, v64
	v_mov_b32_e32 v73, v64
	v_mov_b32_e32 v74, v64
	v_mov_b32_e32 v75, v64
	v_mov_b32_e32 v76, v64
	v_mov_b32_e32 v77, v64
	v_mov_b32_e32 v78, v64
	v_mov_b32_e32 v79, v64
	v_mov_b32_e32 v80, v64
	v_mov_b32_e32 v81, v64
	v_mov_b32_e32 v82, v64
	v_mov_b32_e32 v83, v64
	v_mov_b32_e32 v84, v64
	v_mov_b32_e32 v85, v64
	v_mov_b32_e32 v86, v64
	v_mov_b32_e32 v87, v64
	v_mov_b32_e32 v88, v64
	v_mov_b32_e32 v89, v64
	v_mov_b32_e32 v90, v64
	v_mov_b32_e32 v91, v64
	v_mov_b32_e32 v92, v64
	v_mov_b32_e32 v93, v64
	v_mov_b32_e32 v94, v64
	v_mov_b32_e32 v95, v64
	v_mov_b32_e32 v96, v64
	v_mov_b32_e32 v97, v64
	v_mov_b32_e32 v98, v64
	v_mov_b32_e32 v99, v64
	v_mov_b32_e32 v100, v64
	v_mov_b32_e32 v101, v64
	v_mov_b32_e32 v102, v64
	v_mov_b32_e32 v103, v64
	v_mov_b32_e32 v104, v64
	v_mov_b32_e32 v105, v64
	v_mov_b32_e32 v106, v64
	v_mov_b32_e32 v107, v64
	v_mov_b32_e32 v108, v64
	v_mov_b32_e32 v109, v64
	v_mov_b32_e32 v110, v64
	v_mov_b32_e32 v111, v64
	v_mov_b32_e32 v112, v64
	v_mov_b32_e32 v113, v64
	v_mov_b32_e32 v114, v64
	v_mov_b32_e32 v115, v64
	v_mov_b32_e32 v116, v64
	v_mov_b32_e32 v117, v64
	v_mov_b32_e32 v118, v64
	v_mov_b32_e32 v119, v64
	v_mov_b32_e32 v120, v64
	v_mov_b32_e32 v121, v64
	v_mov_b32_e32 v122, v64
	v_mov_b32_e32 v123, v64
	v_mov_b32_e32 v124, v64
	v_mov_b32_e32 v125, v64
	v_mov_b32_e32 v126, v64
	v_mov_b32_e32 v127, v64
	v_add_u32_e32 v141, 0x10800, v138
	global_load_dwordx4 v[142:145], v[134:135], off offset:416
	v_mov_b32_e32 v158, v136
	v_mov_b32_e32 v159, v137
	v_mov_b32_e32 v225, v212
	v_mov_b32_e32 v138, v213
	ds_read_b128 v[146:149], v141 offset:0
	ds_read_b128 v[134:137], v141 offset:16896
	ds_read_b128 v[210:213], v141 offset:33792
	s_waitcnt vmcnt(1)
; #define LAS __attribute__((address_space(3)))
; __device__ __forceinline__ f32x16 mfma32(bf16x8 a, bf16x8 b, f32x16 c) { return __builtin_amdgcn_mfma_f32_32x32x16_bf16(a, b, c, 0, 0, 0); }
; __device__ void attn_item(const bf16_t* __restrict__ QX, const bf16_t* __restrict__ KV, bf16_t* __restrict__ O, int tt, int head, LAS unsigned char* lds) {
;     ...
; #pragma unroll 4
;     for (int ks = 0; ks < 16; ++ks) {
;       const bf16x8 B = *(const bf16x8*)(qp + 16 * ks);
; #pragma unroll
;       for (int mt = 0; mt < 4; ++mt) sc[mt] = mfma32(*(const LAS bf16x8*)(lds + ((hf * 4 + mt) * 32 + il) * KS + (16 * ks + 8 * h) * 2), B, sc[mt]);
;     }
	s_waitcnt lgkmcnt(2)
	v_mfma_f32_32x32x16_bf16 v[112:127], v[146:149], v[150:153], v[112:127]
	ds_read_b128 v[146:149], v141 offset:50688
	s_waitcnt lgkmcnt(2)
	v_mfma_f32_32x32x16_bf16 v[96:111], v[134:137], v[150:153], v[96:111]
	ds_read_b128 v[134:137], v141 offset:32
	s_waitcnt lgkmcnt(2)
	v_mfma_f32_32x32x16_bf16 v[80:95], v[210:213], v[150:153], v[80:95]
	ds_read_b128 v[210:213], v141 offset:16928
	s_waitcnt lgkmcnt(2)
	v_mfma_f32_32x32x16_bf16 v[64:79], v[146:149], v[150:153], v[64:79]
	ds_read_b128 v[146:149], v141 offset:33824
	s_waitcnt vmcnt(1)
	s_waitcnt lgkmcnt(2)
	v_mfma_f32_32x32x16_bf16 v[112:127], v[134:137], v[154:157], v[112:127]
	ds_read_b128 v[134:137], v141 offset:50720
	s_waitcnt lgkmcnt(2)
	v_mfma_f32_32x32x16_bf16 v[96:111], v[210:213], v[154:157], v[96:111]
	ds_read_b128 v[210:213], v141 offset:64
	s_waitcnt lgkmcnt(2)
	v_mfma_f32_32x32x16_bf16 v[80:95], v[146:149], v[154:157], v[80:95]
	ds_read_b128 v[146:149], v141 offset:16960
	s_waitcnt lgkmcnt(2)
	v_mfma_f32_32x32x16_bf16 v[64:79], v[134:137], v[154:157], v[64:79]
	ds_read_b128 v[134:137], v141 offset:33856
	s_waitcnt vmcnt(1)
	s_waitcnt lgkmcnt(2)
	v_mfma_f32_32x32x16_bf16 v[112:127], v[210:213], v[174:177], v[112:127]
	ds_read_b128 v[210:213], v141 offset:50752
	s_waitcnt lgkmcnt(2)
	v_mfma_f32_32x32x16_bf16 v[96:111], v[146:149], v[174:177], v[96:111]
	ds_read_b128 v[146:149], v141 offset:96
	s_waitcnt lgkmcnt(2)
	v_mfma_f32_32x32x16_bf16 v[80:95], v[134:137], v[174:177], v[80:95]
	ds_read_b128 v[134:137], v141 offset:16992
	s_waitcnt lgkmcnt(2)
	v_mfma_f32_32x32x16_bf16 v[64:79], v[210:213], v[174:177], v[64:79]
	ds_read_b128 v[210:213], v141 offset:33888
	s_waitcnt vmcnt(1)
	s_waitcnt lgkmcnt(2)
	v_mfma_f32_32x32x16_bf16 v[112:127], v[146:149], v[178:181], v[112:127]
	ds_read_b128 v[146:149], v141 offset:50784
	s_waitcnt lgkmcnt(2)
	v_mfma_f32_32x32x16_bf16 v[96:111], v[134:137], v[178:181], v[96:111]
	ds_read_b128 v[134:137], v141 offset:128
	s_waitcnt lgkmcnt(2)
	v_mfma_f32_32x32x16_bf16 v[80:95], v[210:213], v[178:181], v[80:95]
	ds_read_b128 v[210:213], v141 offset:17024
	s_waitcnt lgkmcnt(2)
	v_mfma_f32_32x32x16_bf16 v[64:79], v[146:149], v[178:181], v[64:79]
	ds_read_b128 v[146:149], v141 offset:33920
	s_waitcnt vmcnt(1)
	s_waitcnt lgkmcnt(2)
	v_mfma_f32_32x32x16_bf16 v[112:127], v[134:137], v[182:185], v[112:127]
	ds_read_b128 v[134:137], v141 offset:50816
	s_waitcnt lgkmcnt(2)
	v_mfma_f32_32x32x16_bf16 v[96:111], v[210:213], v[182:185], v[96:111]
	ds_read_b128 v[210:213], v141 offset:160
	s_waitcnt lgkmcnt(2)
	v_mfma_f32_32x32x16_bf16 v[80:95], v[146:149], v[182:185], v[80:95]
	ds_read_b128 v[146:149], v141 offset:17056
	s_waitcnt lgkmcnt(2)
	v_mfma_f32_32x32x16_bf16 v[64:79], v[134:137], v[182:185], v[64:79]
	ds_read_b128 v[134:137], v141 offset:33952
	s_waitcnt vmcnt(1)
	s_waitcnt lgkmcnt(2)
	v_mfma_f32_32x32x16_bf16 v[112:127], v[210:213], v[186:189], v[112:127]
	ds_read_b128 v[210:213], v141 offset:50848
	s_waitcnt lgkmcnt(2)
	v_mfma_f32_32x32x16_bf16 v[96:111], v[146:149], v[186:189], v[96:111]
	ds_read_b128 v[146:149], v141 offset:192
	s_waitcnt lgkmcnt(2)
	v_mfma_f32_32x32x16_bf16 v[80:95], v[134:137], v[186:189], v[80:95]
	ds_read_b128 v[134:137], v141 offset:17088
	s_waitcnt lgkmcnt(2)
	v_mfma_f32_32x32x16_bf16 v[64:79], v[210:213], v[186:189], v[64:79]
	ds_read_b128 v[210:213], v141 offset:33984
	s_waitcnt vmcnt(1)
	s_waitcnt lgkmcnt(2)
	v_mfma_f32_32x32x16_bf16 v[112:127], v[146:149], v[190:193], v[112:127]
	ds_read_b128 v[146:149], v141 offset:50880
	s_waitcnt lgkmcnt(2)
	v_mfma_f32_32x32x16_bf16 v[96:111], v[134:137], v[190:193], v[96:111]
	ds_read_b128 v[134:137], v141 offset:224
	s_waitcnt lgkmcnt(2)
	v_mfma_f32_32x32x16_bf16 v[80:95], v[210:213], v[190:193], v[80:95]
	ds_read_b128 v[210:213], v141 offset:17120
	s_waitcnt lgkmcnt(2)
	v_mfma_f32_32x32x16_bf16 v[64:79], v[146:149], v[190:193], v[64:79]
	ds_read_b128 v[146:149], v141 offset:34016
	s_waitcnt vmcnt(1)
	s_waitcnt lgkmcnt(2)
	v_mfma_f32_32x32x16_bf16 v[112:127], v[134:137], v[194:197], v[112:127]
	ds_read_b128 v[134:137], v141 offset:50912
	s_waitcnt lgkmcnt(2)
	v_mfma_f32_32x32x16_bf16 v[96:111], v[210:213], v[194:197], v[96:111]
	ds_read_b128 v[210:213], v141 offset:256
	s_waitcnt lgkmcnt(2)
	v_mfma_f32_32x32x16_bf16 v[80:95], v[146:149], v[194:197], v[80:95]
	ds_read_b128 v[146:149], v141 offset:17152
	s_waitcnt lgkmcnt(2)
	v_mfma_f32_32x32x16_bf16 v[64:79], v[134:137], v[194:197], v[64:79]
	ds_read_b128 v[134:137], v141 offset:34048
	s_waitcnt vmcnt(1)
	s_waitcnt lgkmcnt(2)
	v_mfma_f32_32x32x16_bf16 v[112:127], v[210:213], v[198:201], v[112:127]
	ds_read_b128 v[210:213], v141 offset:50944
	s_waitcnt lgkmcnt(2)
	v_mfma_f32_32x32x16_bf16 v[96:111], v[146:149], v[198:201], v[96:111]
	ds_read_b128 v[146:149], v141 offset:288
	s_waitcnt lgkmcnt(2)
	v_mfma_f32_32x32x16_bf16 v[80:95], v[134:137], v[198:201], v[80:95]
	ds_read_b128 v[134:137], v141 offset:17184
	s_waitcnt lgkmcnt(2)
	v_mfma_f32_32x32x16_bf16 v[64:79], v[210:213], v[198:201], v[64:79]
	ds_read_b128 v[210:213], v141 offset:34080
	s_waitcnt vmcnt(1)
	s_waitcnt lgkmcnt(2)
	v_mfma_f32_32x32x16_bf16 v[112:127], v[146:149], v[202:205], v[112:127]
	ds_read_b128 v[146:149], v141 offset:50976
	s_waitcnt lgkmcnt(2)
	v_mfma_f32_32x32x16_bf16 v[96:111], v[134:137], v[202:205], v[96:111]
	ds_read_b128 v[134:137], v141 offset:320
	s_waitcnt lgkmcnt(2)
	v_mfma_f32_32x32x16_bf16 v[80:95], v[210:213], v[202:205], v[80:95]
	ds_read_b128 v[210:213], v141 offset:17216
	s_waitcnt lgkmcnt(2)
	v_mfma_f32_32x32x16_bf16 v[64:79], v[146:149], v[202:205], v[64:79]
	ds_read_b128 v[146:149], v141 offset:34112
	s_waitcnt vmcnt(1)
; #define LAS __attribute__((address_space(3)))
; __device__ __forceinline__ unsigned cvt_pk_bf16(float lo, float hi) { f32x2 v = {lo, hi}; bf16x2_t b = __builtin_convertvector(v, bf16x2_t); return __builtin_bit_cast(unsigned, b); }
; __device__ __forceinline__ f32x16 mfma32(bf16x8 a, bf16x8 b, f32x16 c) { return __builtin_amdgcn_mfma_f32_32x32x16_bf16(a, b, c, 0, 0, 0); }
; __device__ void attn_item(const bf16_t* __restrict__ QX, const bf16_t* __restrict__ KV, bf16_t* __restrict__ O, int tt, int head, LAS unsigned char* lds) {
;     ...
; #pragma unroll 4
;     for (int ks = 0; ks < 16; ++ks) {
;       const bf16x8 B = *(const bf16x8*)(qp + 16 * ks);
; #pragma unroll
;       for (int mt = 0; mt < 4; ++mt) sc[mt] = mfma32(*(const LAS bf16x8*)(lds + ((hf * 4 + mt) * 32 + il) * KS + (16 * ks + 8 * h) * 2), B, sc[mt]);
;     }
;     ...
;     for (int mt = 0; mt < 4; ++mt) {
;       u32x4 p0, p1;
; #pragma unroll
;       for (int r = 0; r < 16; r += 2) {
;         const float e0 = __builtin_amdgcn_exp2f((sc[mt][r] - mx) * 1.4426950408889634f), e1 = __builtin_amdgcn_exp2f((sc[mt][r + 1] - mx) * 1.4426950408889634f);
;         sum += e0 + e1; const unsigned pk = cvt_pk_bf16(e0, e1);
;         if (r < 8) p0[r >> 1] = pk; else p1[(r - 8) >> 1] = pk;
;       }
;       pf[hf * 4 + mt][0] = (bf16x8)p0; pf[hf * 4 + mt][1] = (bf16x8)p1;
	s_waitcnt lgkmcnt(2)
	v_mfma_f32_32x32x16_bf16 v[112:127], v[134:137], v[206:209], v[112:127]
	ds_read_b128 v[134:137], v141 offset:51008
	s_waitcnt lgkmcnt(2)
	v_mfma_f32_32x32x16_bf16 v[96:111], v[210:213], v[206:209], v[96:111]
	ds_read_b128 v[210:213], v141 offset:352
	s_waitcnt lgkmcnt(2)
	v_mfma_f32_32x32x16_bf16 v[80:95], v[146:149], v[206:209], v[80:95]
	ds_read_b128 v[146:149], v141 offset:17248
	s_waitcnt lgkmcnt(2)
	v_mfma_f32_32x32x16_bf16 v[64:79], v[134:137], v[206:209], v[64:79]
	ds_read_b128 v[134:137], v141 offset:34144
	s_waitcnt vmcnt(1)
	s_waitcnt lgkmcnt(2)
	v_mfma_f32_32x32x16_bf16 v[112:127], v[210:213], v[226:229], v[112:127]
	ds_read_b128 v[210:213], v141 offset:51040
	s_waitcnt lgkmcnt(2)
	v_mfma_f32_32x32x16_bf16 v[96:111], v[146:149], v[226:229], v[96:111]
	ds_read_b128 v[146:149], v141 offset:384
	s_waitcnt lgkmcnt(2)
	v_mfma_f32_32x32x16_bf16 v[80:95], v[134:137], v[226:229], v[80:95]
	ds_read_b128 v[134:137], v141 offset:17280
	s_waitcnt lgkmcnt(2)
	v_mfma_f32_32x32x16_bf16 v[64:79], v[210:213], v[226:229], v[64:79]
	ds_read_b128 v[210:213], v141 offset:34176
	s_waitcnt vmcnt(1)
	s_waitcnt lgkmcnt(2)
	v_mfma_f32_32x32x16_bf16 v[112:127], v[146:149], v[232:235], v[112:127]
	ds_read_b128 v[146:149], v141 offset:51072
	s_waitcnt lgkmcnt(2)
	v_mfma_f32_32x32x16_bf16 v[96:111], v[134:137], v[232:235], v[96:111]
	ds_read_b128 v[134:137], v141 offset:416
	s_waitcnt lgkmcnt(2)
	v_mfma_f32_32x32x16_bf16 v[80:95], v[210:213], v[232:235], v[80:95]
	ds_read_b128 v[210:213], v141 offset:17312
	s_waitcnt lgkmcnt(2)
	v_mfma_f32_32x32x16_bf16 v[64:79], v[146:149], v[232:235], v[64:79]
	ds_read_b128 v[146:149], v141 offset:34208
	s_waitcnt vmcnt(1)
	s_waitcnt lgkmcnt(2)
	v_mfma_f32_32x32x16_bf16 v[112:127], v[134:137], v[236:239], v[112:127]
	ds_read_b128 v[134:137], v141 offset:51104
	s_waitcnt lgkmcnt(2)
	v_mfma_f32_32x32x16_bf16 v[96:111], v[210:213], v[236:239], v[96:111]
	ds_read_b128 v[210:213], v141 offset:448
	s_waitcnt lgkmcnt(2)
	v_mfma_f32_32x32x16_bf16 v[80:95], v[146:149], v[236:239], v[80:95]
	ds_read_b128 v[146:149], v141 offset:17344
	s_waitcnt lgkmcnt(2)
	v_mfma_f32_32x32x16_bf16 v[64:79], v[134:137], v[236:239], v[64:79]
	ds_read_b128 v[134:137], v141 offset:34240
	s_waitcnt vmcnt(1)
	s_waitcnt lgkmcnt(2)
	v_mfma_f32_32x32x16_bf16 v[112:127], v[210:213], v[240:243], v[112:127]
	ds_read_b128 v[210:213], v141 offset:51136
	s_waitcnt lgkmcnt(2)
	v_mfma_f32_32x32x16_bf16 v[96:111], v[146:149], v[240:243], v[96:111]
	ds_read_b128 v[146:149], v141 offset:480
	s_waitcnt lgkmcnt(2)
	v_mfma_f32_32x32x16_bf16 v[80:95], v[134:137], v[240:243], v[80:95]
	ds_read_b128 v[134:137], v141 offset:17376
	s_waitcnt lgkmcnt(2)
	v_mfma_f32_32x32x16_bf16 v[64:79], v[210:213], v[240:243], v[64:79]
	ds_read_b128 v[210:213], v141 offset:34272
	s_waitcnt vmcnt(0)
	s_waitcnt lgkmcnt(2)
	v_mfma_f32_32x32x16_bf16 v[112:127], v[146:149], v[142:145], v[112:127]
	ds_read_b128 v[146:149], v141 offset:51168
	s_waitcnt lgkmcnt(2)
	v_mfma_f32_32x32x16_bf16 v[96:111], v[134:137], v[142:145], v[96:111]
	s_waitcnt lgkmcnt(1)
	v_mfma_f32_32x32x16_bf16 v[80:95], v[210:213], v[142:145], v[80:95]
	s_waitcnt lgkmcnt(0)
	v_mfma_f32_32x32x16_bf16 v[64:79], v[146:149], v[142:145], v[64:79]
	v_mov_b32_e32 v136, v158
	v_mov_b32_e32 v137, v159
	v_mov_b32_e32 v212, v225
	v_mov_b32_e32 v213, v138
	s_movk_i32 s12, 0x200
	v_max_f32_e32 v134, v140, v140
	v_max_f32_e32 v135, v139, v139
	v_max_f32_e32 v152, v135, v134
	v_sub_f32_e32 v0, v0, v152
	v_sub_f32_e32 v48, v48, v152
	v_sub_f32_e32 v49, v49, v152
	v_mul_f32_e32 v0, 0x3fb8aa3b, v0
	v_mul_f32_e32 v48, 0x3fb8aa3b, v48
	v_mul_f32_e32 v49, 0x3fb8aa3b, v49
	v_sub_f32_e32 v50, v50, v152
	v_sub_f32_e32 v51, v51, v152
	v_exp_f32_e32 v134, v0
	v_sub_f32_e32 v0, v1, v152
	v_exp_f32_e32 v48, v48
	v_exp_f32_e32 v49, v49
	v_mul_f32_e32 v50, 0x3fb8aa3b, v50
	v_mul_f32_e32 v51, 0x3fb8aa3b, v51
	v_sub_f32_e32 v52, v52, v152
	v_sub_f32_e32 v53, v53, v152
	v_mul_f32_e32 v0, 0x3fb8aa3b, v0
	v_exp_f32_e32 v50, v50
	v_exp_f32_e32 v51, v51
	v_mul_f32_e32 v52, 0x3fb8aa3b, v52
	v_mul_f32_e32 v53, 0x3fb8aa3b, v53
	v_sub_f32_e32 v54, v54, v152
	v_sub_f32_e32 v55, v55, v152
	v_exp_f32_e32 v135, v0
	v_sub_f32_e32 v0, v2, v152
	v_exp_f32_e32 v52, v52
	v_exp_f32_e32 v53, v53
	v_mul_f32_e32 v54, 0x3fb8aa3b, v54
	v_mul_f32_e32 v55, 0x3fb8aa3b, v55
	v_sub_f32_e32 v56, v56, v152
	v_sub_f32_e32 v57, v57, v152
	v_mul_f32_e32 v0, 0x3fb8aa3b, v0
	v_exp_f32_e32 v54, v54
	v_exp_f32_e32 v55, v55
	v_mul_f32_e32 v56, 0x3fb8aa3b, v56
	v_mul_f32_e32 v57, 0x3fb8aa3b, v57
	v_sub_f32_e32 v58, v58, v152
	v_sub_f32_e32 v59, v59, v152
	v_exp_f32_e32 v138, v0
	v_sub_f32_e32 v0, v3, v152
	v_add_f32_e32 v153, v48, v49
	v_exp_f32_e32 v56, v56
	v_exp_f32_e32 v57, v57
	v_mul_f32_e32 v58, 0x3fb8aa3b, v58
	v_mul_f32_e32 v59, 0x3fb8aa3b, v59
	v_sub_f32_e32 v60, v60, v152
	v_sub_f32_e32 v61, v61, v152
	v_mul_f32_e32 v0, 0x3fb8aa3b, v0
	v_add_f32_e32 v154, v50, v51
	v_exp_f32_e32 v58, v58
	v_exp_f32_e32 v59, v59
	v_mul_f32_e32 v60, 0x3fb8aa3b, v60
	v_mul_f32_e32 v61, 0x3fb8aa3b, v61
	v_sub_f32_e32 v62, v62, v152
	v_sub_f32_e32 v63, v63, v152
	v_exp_f32_e32 v139, v0
	v_sub_f32_e32 v0, v4, v152
	v_sub_f32_e32 v4, v8, v152
	v_add_f32_e32 v8, 0, v153
	v_add_f32_e32 v155, v52, v53
	v_exp_f32_e32 v60, v60
	v_exp_f32_e32 v61, v61
	v_mul_f32_e32 v62, 0x3fb8aa3b, v62
	v_mul_f32_e32 v63, 0x3fb8aa3b, v63
	v_sub_f32_e32 v32, v32, v152
	v_sub_f32_e32 v33, v33, v152
	v_add_f32_e32 v8, v154, v8
	v_add_f32_e32 v156, v54, v55
	v_exp_f32_e32 v62, v62
	v_exp_f32_e32 v63, v63
	v_mul_f32_e32 v32, 0x3fb8aa3b, v32
	v_mul_f32_e32 v33, 0x3fb8aa3b, v33
	v_sub_f32_e32 v34, v34, v152
; __device__ __forceinline__ unsigned cvt_pk_bf16(float lo, float hi) { f32x2 v = {lo, hi}; bf16x2_t b = __builtin_convertvector(v, bf16x2_t); return __builtin_bit_cast(unsigned, b); }
; __device__ void attn_item(const bf16_t* __restrict__ QX, const bf16_t* __restrict__ KV, bf16_t* __restrict__ O, int tt, int head, LAS unsigned char* lds) {
;     ...
; #pragma unroll
;     for (int mt = 0; mt < 4; ++mt)
; #pragma unroll
;       for (int r = 0; r < 16; ++r) mx = fmaxf(mx, sc[mt][r]);
;     mx = fmaxf(mx, __shfl_xor(mx, 32));
;     ...
;       for (int r = 0; r < 16; r += 2) {
;         const float e0 = __builtin_amdgcn_exp2f((sc[mt][r] - mx) * 1.4426950408889634f), e1 = __builtin_amdgcn_exp2f((sc[mt][r + 1] - mx) * 1.4426950408889634f);
;         sum += e0 + e1; const unsigned pk = cvt_pk_bf16(e0, e1);
;         if (r < 8) p0[r >> 1] = pk; else p1[(r - 8) >> 1] = pk;
	v_sub_f32_e32 v35, v35, v152
	v_add_f32_e32 v8, v155, v8
	v_add_f32_e32 v157, v56, v57
	v_exp_f32_e32 v32, v32
	v_exp_f32_e32 v33, v33
	v_mul_f32_e32 v34, 0x3fb8aa3b, v34
	v_mul_f32_e32 v35, 0x3fb8aa3b, v35
	v_sub_f32_e32 v36, v36, v152
	v_sub_f32_e32 v37, v37, v152
	v_add_f32_e32 v8, v156, v8
	v_add_f32_e32 v158, v58, v59
	v_exp_f32_e32 v34, v34
	v_exp_f32_e32 v35, v35
	v_mul_f32_e32 v36, 0x3fb8aa3b, v36
	v_mul_f32_e32 v37, 0x3fb8aa3b, v37
	v_sub_f32_e32 v38, v38, v152
	v_sub_f32_e32 v39, v39, v152
	v_add_f32_e32 v8, v157, v8
	v_add_f32_e32 v159, v60, v61
	v_exp_f32_e32 v36, v36
	v_exp_f32_e32 v37, v37
	v_mul_f32_e32 v38, 0x3fb8aa3b, v38
	v_mul_f32_e32 v39, 0x3fb8aa3b, v39
	v_sub_f32_e32 v40, v40, v152
	v_sub_f32_e32 v41, v41, v152
	v_add_f32_e32 v8, v158, v8
	v_add_f32_e32 v174, v62, v63
	v_exp_f32_e32 v38, v38
	v_exp_f32_e32 v39, v39
	v_mul_f32_e32 v40, 0x3fb8aa3b, v40
	v_mul_f32_e32 v41, 0x3fb8aa3b, v41
	v_sub_f32_e32 v42, v42, v152
	v_sub_f32_e32 v43, v43, v152
	v_add_f32_e32 v8, v159, v8
	v_add_f32_e32 v175, v32, v33
	v_exp_f32_e32 v40, v40
	v_exp_f32_e32 v41, v41
	v_mul_f32_e32 v42, 0x3fb8aa3b, v42
	v_mul_f32_e32 v43, 0x3fb8aa3b, v43
	v_sub_f32_e32 v44, v44, v152
	v_sub_f32_e32 v45, v45, v152
	v_add_f32_e32 v8, v174, v8
	v_add_f32_e32 v176, v34, v35
	v_exp_f32_e32 v42, v42
	v_exp_f32_e32 v43, v43
	v_mul_f32_e32 v44, 0x3fb8aa3b, v44
	v_mul_f32_e32 v45, 0x3fb8aa3b, v45
	v_sub_f32_e32 v46, v46, v152
	v_sub_f32_e32 v47, v47, v152
	v_add_f32_e32 v8, v175, v8
	v_add_f32_e32 v177, v36, v37
	v_exp_f32_e32 v44, v44
	v_exp_f32_e32 v45, v45
	v_mul_f32_e32 v46, 0x3fb8aa3b, v46
	v_mul_f32_e32 v47, 0x3fb8aa3b, v47
	v_sub_f32_e32 v16, v16, v152
	v_sub_f32_e32 v17, v17, v152
	v_add_f32_e32 v8, v176, v8
	v_add_f32_e32 v178, v38, v39
	v_exp_f32_e32 v46, v46
	v_exp_f32_e32 v47, v47
	v_mul_f32_e32 v16, 0x3fb8aa3b, v16
	v_mul_f32_e32 v17, 0x3fb8aa3b, v17
	v_sub_f32_e32 v18, v18, v152
	v_sub_f32_e32 v19, v19, v152
	v_add_f32_e32 v8, v177, v8
	v_add_f32_e32 v179, v40, v41
	v_exp_f32_e32 v16, v16
	v_exp_f32_e32 v17, v17
	v_mul_f32_e32 v18, 0x3fb8aa3b, v18
	v_mul_f32_e32 v19, 0x3fb8aa3b, v19
	v_sub_f32_e32 v20, v20, v152
	v_sub_f32_e32 v21, v21, v152
	v_add_f32_e32 v8, v178, v8
	v_add_f32_e32 v180, v42, v43
	v_exp_f32_e32 v18, v18
	v_exp_f32_e32 v19, v19
	v_mul_f32_e32 v20, 0x3fb8aa3b, v20
	v_mul_f32_e32 v21, 0x3fb8aa3b, v21
	v_sub_f32_e32 v22, v22, v152
	v_sub_f32_e32 v23, v23, v152
	v_add_f32_e32 v8, v179, v8
	v_add_f32_e32 v181, v44, v45
	v_exp_f32_e32 v20, v20
	v_exp_f32_e32 v21, v21
	v_mul_f32_e32 v22, 0x3fb8aa3b, v22
	v_mul_f32_e32 v23, 0x3fb8aa3b, v23
	v_sub_f32_e32 v24, v24, v152
	v_sub_f32_e32 v25, v25, v152
	v_add_f32_e32 v8, v180, v8
	v_add_f32_e32 v182, v46, v47
	v_exp_f32_e32 v22, v22
	v_exp_f32_e32 v23, v23
	v_mul_f32_e32 v24, 0x3fb8aa3b, v24
	v_mul_f32_e32 v25, 0x3fb8aa3b, v25
	v_sub_f32_e32 v26, v26, v152
	v_sub_f32_e32 v27, v27, v152
	v_add_f32_e32 v8, v181, v8
	v_add_f32_e32 v183, v16, v17
	v_exp_f32_e32 v24, v24
	v_exp_f32_e32 v25, v25
	v_mul_f32_e32 v26, 0x3fb8aa3b, v26
	v_mul_f32_e32 v27, 0x3fb8aa3b, v27
	v_sub_f32_e32 v28, v28, v152
	v_sub_f32_e32 v29, v29, v152
	v_add_f32_e32 v8, v182, v8
	v_add_f32_e32 v184, v18, v19
	v_exp_f32_e32 v26, v26
	v_exp_f32_e32 v27, v27
	v_mul_f32_e32 v28, 0x3fb8aa3b, v28
	v_mul_f32_e32 v29, 0x3fb8aa3b, v29
	v_sub_f32_e32 v30, v30, v152
	v_sub_f32_e32 v31, v31, v152
	v_mul_f32_e32 v0, 0x3fb8aa3b, v0
	v_add_f32_e32 v8, v183, v8
	v_add_f32_e32 v185, v20, v21
	v_exp_f32_e32 v28, v28
	v_exp_f32_e32 v29, v29
	v_mul_f32_e32 v30, 0x3fb8aa3b, v30
	v_mul_f32_e32 v31, 0x3fb8aa3b, v31
	v_exp_f32_e32 v140, v0
	v_sub_f32_e32 v0, v5, v152
	v_add_f32_e32 v8, v184, v8
	v_add_f32_e32 v186, v22, v23
	v_exp_f32_e32 v30, v30
	v_exp_f32_e32 v31, v31
	v_mul_f32_e32 v0, 0x3fb8aa3b, v0
	v_add_f32_e32 v8, v185, v8
	v_add_f32_e32 v187, v24, v25
	v_exp_f32_e32 v141, v0
	v_sub_f32_e32 v0, v6, v152
	v_add_f32_e32 v8, v186, v8
	v_add_f32_e32 v188, v26, v27
	v_mul_f32_e32 v0, 0x3fb8aa3b, v0
	v_add_f32_e32 v8, v187, v8
	v_add_f32_e32 v189, v28, v29
	v_exp_f32_e32 v142, v0
	v_sub_f32_e32 v0, v7, v152
	v_add_f32_e32 v8, v188, v8
	v_add_f32_e32 v190, v30, v31
	v_mul_f32_e32 v0, 0x3fb8aa3b, v0
	v_add_f32_e32 v8, v189, v8
	v_exp_f32_e32 v143, v0
	v_add_f32_e32 v0, v134, v135
	v_add_f32_e32 v8, v190, v8
	v_add_f32_e32 v1, v138, v139
	v_add_f32_e32 v0, v0, v8
	v_add_f32_e32 v0, v1, v0
	v_max3_f32 v1, v152, v112, v113
	v_max3_f32 v1, v1, v114, v115
	v_max3_f32 v1, v1, v116, v117
	v_max3_f32 v1, v1, v118, v119
	v_max3_f32 v1, v1, v120, v121
	v_max3_f32 v1, v1, v122, v123
	v_max3_f32 v1, v1, v124, v125
	v_max3_f32 v1, v1, v126, v127
	v_max3_f32 v1, v1, v96, v97
	v_max3_f32 v1, v1, v98, v99
	v_max3_f32 v1, v1, v100, v101
	v_max3_f32 v1, v1, v102, v103
	v_max3_f32 v1, v1, v104, v105
	v_max3_f32 v1, v1, v106, v107
	v_max3_f32 v1, v1, v108, v109
	v_max3_f32 v1, v1, v110, v111
	v_max3_f32 v1, v1, v80, v81
	v_max3_f32 v1, v1, v82, v83
	v_max3_f32 v1, v1, v84, v85
	v_mul_f32_e32 v4, 0x3fb8aa3b, v4
	v_max3_f32 v1, v1, v86, v87
	v_exp_f32_e32 v144, v4
	v_sub_f32_e32 v4, v9, v152
	v_max3_f32 v1, v1, v88, v89
	v_mul_f32_e32 v4, 0x3fb8aa3b, v4
	v_max3_f32 v1, v1, v90, v91
	v_exp_f32_e32 v145, v4
	v_sub_f32_e32 v4, v10, v152
	v_max3_f32 v1, v1, v92, v93
	v_mul_f32_e32 v4, 0x3fb8aa3b, v4
	v_max3_f32 v1, v1, v94, v95
	v_exp_f32_e32 v146, v4
	v_sub_f32_e32 v4, v11, v152
	v_max3_f32 v1, v1, v64, v65
	v_mul_f32_e32 v4, 0x3fb8aa3b, v4
	v_max3_f32 v1, v1, v66, v67
	v_exp_f32_e32 v147, v4
	v_sub_f32_e32 v4, v12, v152
	v_max3_f32 v1, v1, v68, v69
	v_mul_f32_e32 v4, 0x3fb8aa3b, v4
	v_max3_f32 v1, v1, v70, v71
	v_exp_f32_e32 v148, v4
	v_sub_f32_e32 v4, v13, v152
	v_max3_f32 v1, v1, v72, v73
	v_mul_f32_e32 v4, 0x3fb8aa3b, v4
	v_max3_f32 v1, v1, v74, v75
	v_exp_f32_e32 v149, v4
	v_sub_f32_e32 v4, v14, v152
	v_max3_f32 v1, v1, v76, v77
	v_add_f32_e32 v2, v140, v141
	v_mul_f32_e32 v4, 0x3fb8aa3b, v4
	v_max3_f32 v1, v1, v78, v79
	v_exp_f32_e32 v150, v4
	v_sub_f32_e32 v4, v15, v152
	v_add_f32_e32 v0, v2, v0
	ds_bpermute_b32 v2, v137, v1
	v_add_f32_e32 v3, v142, v143
	v_mul_f32_e32 v4, 0x3fb8aa3b, v4
	v_exp_f32_e32 v151, v4
	v_add_f32_e32 v4, v144, v145
	v_add_f32_e32 v0, v3, v0
	v_add_f32_e32 v5, v146, v147
	v_add_f32_e32 v0, v4, v0
	v_add_f32_e32 v6, v148, v149
	v_add_f32_e32 v0, v5, v0
	v_add_f32_e32 v5, v6, v0
	s_waitcnt lgkmcnt(0)
; __device__ __forceinline__ unsigned cvt_pk_bf16(float lo, float hi) { f32x2 v = {lo, hi}; bf16x2_t b = __builtin_convertvector(v, bf16x2_t); return __builtin_bit_cast(unsigned, b); }
; __device__ void attn_item(const bf16_t* __restrict__ QX, const bf16_t* __restrict__ KV, bf16_t* __restrict__ O, int tt, int head, LAS unsigned char* lds) {
;     ...
;     mx = fmaxf(mx, __shfl_xor(mx, 32));
;     if (hf == 1) { const float f = __builtin_amdgcn_exp2f((mxp - mx) * 1.4426950408889634f); sum *= f;
; #pragma unroll
;       for (int mt = 0; mt < 4; ++mt) { pf[mt][0] = scale_frag(pf[mt][0], f); pf[mt][1] = scale_frag(pf[mt][1], f); } }
; #pragma unroll
;     for (int mt = 0; mt < 4; ++mt) {
;       u32x4 p0, p1;
; #pragma unroll
;       for (int r = 0; r < 16; r += 2) {
;         const float e0 = __builtin_amdgcn_exp2f((sc[mt][r] - mx) * 1.4426950408889634f), e1 = __builtin_amdgcn_exp2f((sc[mt][r + 1] - mx) * 1.4426950408889634f);
;         sum += e0 + e1; const unsigned pk = cvt_pk_bf16(e0, e1);
;         if (r < 8) p0[r >> 1] = pk; else p1[(r - 8) >> 1] = pk;
;       }
;       pf[hf * 4 + mt][0] = (bf16x8)p0; pf[hf * 4 + mt][1] = (bf16x8)p1;
	v_max_f32_e32 v0, v2, v2
	v_max_f32_e32 v182, v1, v0
	v_sub_f32_e32 v1, v112, v182
	v_sub_f32_e32 v2, v113, v182
	v_sub_f32_e32 v0, v152, v182
	v_mul_f32_e32 v1, 0x3fb8aa3b, v1
	v_mul_f32_e32 v2, 0x3fb8aa3b, v2
	v_mul_f32_e32 v0, 0x3fb8aa3b, v0
	v_exp_f32_e32 v1, v1
	v_exp_f32_e32 v2, v2
	v_exp_f32_e32 v0, v0
	v_add_f32_e32 v7, v150, v151
	v_sub_f32_e32 v3, v114, v182
	v_sub_f32_e32 v4, v115, v182
	v_add_f32_e32 v5, v7, v5
	v_add_f32_e32 v9, v1, v2
	v_mul_f32_e32 v3, 0x3fb8aa3b, v3
	v_mul_f32_e32 v4, 0x3fb8aa3b, v4
	v_fmac_f32_e32 v9, v5, v0
	v_sub_f32_e32 v5, v116, v182
	v_sub_f32_e32 v6, v117, v182
	v_exp_f32_e32 v3, v3
	v_exp_f32_e32 v4, v4
	v_mul_f32_e32 v5, 0x3fb8aa3b, v5
	v_mul_f32_e32 v6, 0x3fb8aa3b, v6
	v_exp_f32_e32 v5, v5
	v_exp_f32_e32 v6, v6
	v_add_f32_e32 v10, v3, v4
	v_sub_f32_e32 v7, v118, v182
	v_sub_f32_e32 v8, v119, v182
	v_add_f32_e32 v9, v10, v9
	v_add_f32_e32 v10, v5, v6
	v_mul_f32_e32 v7, 0x3fb8aa3b, v7
	v_mul_f32_e32 v8, 0x3fb8aa3b, v8
	v_add_f32_e32 v13, v10, v9
	v_sub_f32_e32 v9, v120, v182
	v_sub_f32_e32 v10, v121, v182
	v_exp_f32_e32 v7, v7
	v_exp_f32_e32 v8, v8
	v_mul_f32_e32 v9, 0x3fb8aa3b, v9
	v_mul_f32_e32 v10, 0x3fb8aa3b, v10
	v_exp_f32_e32 v9, v9
	v_exp_f32_e32 v10, v10
	v_add_f32_e32 v14, v7, v8
	v_sub_f32_e32 v11, v122, v182
	v_sub_f32_e32 v12, v123, v182
	v_add_f32_e32 v13, v14, v13
	v_add_f32_e32 v14, v9, v10
	v_mul_f32_e32 v11, 0x3fb8aa3b, v11
	v_mul_f32_e32 v12, 0x3fb8aa3b, v12
	v_add_f32_e32 v113, v14, v13
	v_sub_f32_e32 v13, v124, v182
	v_sub_f32_e32 v14, v125, v182
	v_exp_f32_e32 v11, v11
	v_exp_f32_e32 v12, v12
	v_mul_f32_e32 v13, 0x3fb8aa3b, v13
	v_mul_f32_e32 v14, 0x3fb8aa3b, v14
	v_exp_f32_e32 v13, v13
	v_exp_f32_e32 v14, v14
	v_add_f32_e32 v114, v11, v12
	v_sub_f32_e32 v96, v96, v182
	v_sub_f32_e32 v15, v126, v182
	v_sub_f32_e32 v112, v127, v182
	v_add_f32_e32 v113, v114, v113
	v_add_f32_e32 v114, v13, v14
	v_mul_f32_e32 v96, 0x3fb8aa3b, v96
	v_mul_f32_e32 v15, 0x3fb8aa3b, v15
	v_mul_f32_e32 v112, 0x3fb8aa3b, v112
	v_add_f32_e32 v117, v114, v113
	v_exp_f32_e32 v113, v96
	v_sub_f32_e32 v96, v97, v182
	v_exp_f32_e32 v15, v15
	v_exp_f32_e32 v112, v112
	v_mul_f32_e32 v96, 0x3fb8aa3b, v96
	v_exp_f32_e32 v114, v96
	v_sub_f32_e32 v96, v98, v182
	v_mul_f32_e32 v96, 0x3fb8aa3b, v96
	v_exp_f32_e32 v115, v96
	v_sub_f32_e32 v96, v99, v182
	v_sub_f32_e32 v98, v100, v182
	v_add_f32_e32 v118, v15, v112
	v_mul_f32_e32 v96, 0x3fb8aa3b, v96
	v_mul_f32_e32 v98, 0x3fb8aa3b, v98
	v_exp_f32_e32 v116, v96
	v_add_f32_e32 v96, v118, v117
	v_exp_f32_e32 v117, v98
	v_sub_f32_e32 v98, v101, v182
	v_mul_f32_e32 v98, 0x3fb8aa3b, v98
	v_exp_f32_e32 v118, v98
	v_sub_f32_e32 v98, v102, v182
	v_sub_f32_e32 v80, v80, v182
	v_mul_f32_e32 v98, 0x3fb8aa3b, v98
	v_mul_f32_e32 v80, 0x3fb8aa3b, v80
	v_exp_f32_e32 v119, v98
	v_sub_f32_e32 v98, v103, v182
	v_exp_f32_e32 v152, v80
	v_sub_f32_e32 v80, v81, v182
	v_mul_f32_e32 v98, 0x3fb8aa3b, v98
	v_mul_f32_e32 v80, 0x3fb8aa3b, v80
	v_exp_f32_e32 v120, v98
	v_sub_f32_e32 v98, v104, v182
	v_exp_f32_e32 v153, v80
	v_sub_f32_e32 v80, v82, v182
	v_sub_f32_e32 v82, v84, v182
	v_mul_f32_e32 v98, 0x3fb8aa3b, v98
	v_mul_f32_e32 v82, 0x3fb8aa3b, v82
	v_exp_f32_e32 v121, v98
	v_sub_f32_e32 v98, v105, v182
	v_exp_f32_e32 v156, v82
	v_sub_f32_e32 v82, v85, v182
	v_mul_f32_e32 v98, 0x3fb8aa3b, v98
	v_mul_f32_e32 v82, 0x3fb8aa3b, v82
	v_exp_f32_e32 v122, v98
	v_sub_f32_e32 v98, v106, v182
	v_exp_f32_e32 v157, v82
	v_sub_f32_e32 v82, v86, v182
	v_sub_f32_e32 v64, v64, v182
	v_mul_f32_e32 v98, 0x3fb8aa3b, v98
	v_mul_f32_e32 v82, 0x3fb8aa3b, v82
	v_mul_f32_e32 v64, 0x3fb8aa3b, v64
	v_exp_f32_e32 v123, v98
	v_sub_f32_e32 v98, v107, v182
	v_exp_f32_e32 v158, v82
	v_sub_f32_e32 v82, v87, v182
	v_exp_f32_e32 v183, v64
	v_sub_f32_e32 v64, v65, v182
	v_mul_f32_e32 v98, 0x3fb8aa3b, v98
	v_mul_f32_e32 v82, 0x3fb8aa3b, v82
	v_mul_f32_e32 v64, 0x3fb8aa3b, v64
	v_exp_f32_e32 v124, v98
	v_sub_f32_e32 v98, v108, v182
	v_exp_f32_e32 v159, v82
	v_sub_f32_e32 v82, v88, v182
	v_exp_f32_e32 v184, v64
	v_sub_f32_e32 v64, v66, v182
	v_sub_f32_e32 v66, v68, v182
	v_mul_f32_e32 v98, 0x3fb8aa3b, v98
	v_mul_f32_e32 v82, 0x3fb8aa3b, v82
	v_mul_f32_e32 v66, 0x3fb8aa3b, v66
	v_exp_f32_e32 v125, v98
	v_sub_f32_e32 v98, v109, v182
	v_exp_f32_e32 v174, v82
	v_sub_f32_e32 v82, v89, v182
	v_exp_f32_e32 v187, v66
	v_sub_f32_e32 v66, v69, v182
	v_mul_f32_e32 v98, 0x3fb8aa3b, v98
	v_mul_f32_e32 v82, 0x3fb8aa3b, v82
	v_mul_f32_e32 v66, 0x3fb8aa3b, v66
	v_exp_f32_e32 v126, v98
	v_sub_f32_e32 v98, v110, v182
	v_exp_f32_e32 v175, v82
	v_sub_f32_e32 v82, v90, v182
	v_exp_f32_e32 v188, v66
	v_sub_f32_e32 v66, v70, v182
	v_add_f32_e32 v97, v113, v114
	v_mul_f32_e32 v98, 0x3fb8aa3b, v98
	v_mul_f32_e32 v82, 0x3fb8aa3b, v82
	v_mul_f32_e32 v66, 0x3fb8aa3b, v66
	v_add_f32_e32 v96, v97, v96
	v_add_f32_e32 v97, v115, v116
	v_exp_f32_e32 v127, v98
	v_sub_f32_e32 v98, v111, v182
	v_exp_f32_e32 v176, v82
	v_sub_f32_e32 v82, v91, v182
	v_exp_f32_e32 v189, v66
	v_sub_f32_e32 v66, v71, v182
	v_add_f32_e32 v96, v97, v96
	v_add_f32_e32 v97, v117, v118
	v_mul_f32_e32 v98, 0x3fb8aa3b, v98
	v_mul_f32_e32 v80, 0x3fb8aa3b, v80
	v_mul_f32_e32 v82, 0x3fb8aa3b, v82
	v_mul_f32_e32 v66, 0x3fb8aa3b, v66
	v_add_f32_e32 v96, v97, v96
	v_add_f32_e32 v97, v119, v120
	v_exp_f32_e32 v111, v98
	v_exp_f32_e32 v154, v80
	v_sub_f32_e32 v80, v83, v182
	v_exp_f32_e32 v177, v82
	v_sub_f32_e32 v82, v92, v182
	v_exp_f32_e32 v190, v66
	v_sub_f32_e32 v66, v72, v182
	v_add_f32_e32 v96, v97, v96
	v_add_f32_e32 v97, v121, v122
	v_mul_f32_e32 v80, 0x3fb8aa3b, v80
	v_mul_f32_e32 v82, 0x3fb8aa3b, v82
	v_mul_f32_e32 v66, 0x3fb8aa3b, v66
	v_add_f32_e32 v96, v97, v96
	v_add_f32_e32 v97, v123, v124
; #define LAS __attribute__((address_space(3)))
; __device__ __forceinline__ unsigned cvt_pk_bf16(float lo, float hi) { f32x2 v = {lo, hi}; bf16x2_t b = __builtin_convertvector(v, bf16x2_t); return __builtin_bit_cast(unsigned, b); }
; __device__ void attn_item(const bf16_t* __restrict__ QX, const bf16_t* __restrict__ KV, bf16_t* __restrict__ O, int tt, int head, LAS unsigned char* lds) {
;     ...
;       for (int r = 0; r < 16; r += 2) {
;         const float e0 = __builtin_amdgcn_exp2f((sc[mt][r] - mx) * 1.4426950408889634f), e1 = __builtin_amdgcn_exp2f((sc[mt][r + 1] - mx) * 1.4426950408889634f);
;         sum += e0 + e1; const unsigned pk = cvt_pk_bf16(e0, e1);
;         if (r < 8) p0[r >> 1] = pk; else p1[(r - 8) >> 1] = pk;
;       }
;       pf[hf * 4 + mt][0] = (bf16x8)p0; pf[hf * 4 + mt][1] = (bf16x8)p1;
;     }
;     mxp = mx;
;   }
;   sum += __shfl_xor(sum, 32);
;   const float inv = __builtin_amdgcn_rcpf(sum);
;   __builtin_amdgcn_sched_barrier(0);
;   __syncthreads();
;   __builtin_amdgcn_sched_barrier(0);
; #pragma unroll 4
;   for (int it = 0; it < 16; ++it) { const int q = tid + it * 512, m = q >> 5, c = q & 31;
;     *(LAS u32x4*)(lds + m * VS + c * 16) = *(const u32x4*)(KV + (size_t)(mrow0 + m) * 2048 + 1024 + head * 256 + c * 8); }
	v_exp_f32_e32 v155, v80
	v_exp_f32_e32 v178, v82
	v_sub_f32_e32 v82, v93, v182
	v_exp_f32_e32 v191, v66
	v_sub_f32_e32 v66, v73, v182
	v_add_f32_e32 v96, v97, v96
	v_add_f32_e32 v97, v125, v126
	v_mul_f32_e32 v82, 0x3fb8aa3b, v82
	v_mul_f32_e32 v66, 0x3fb8aa3b, v66
	v_add_f32_e32 v96, v97, v96
	v_add_f32_e32 v97, v127, v111
	v_exp_f32_e32 v179, v82
	v_sub_f32_e32 v82, v94, v182
	v_exp_f32_e32 v192, v66
	v_sub_f32_e32 v66, v74, v182
	v_add_f32_e32 v80, v97, v96
	v_add_f32_e32 v81, v152, v153
	v_mul_f32_e32 v82, 0x3fb8aa3b, v82
	v_mul_f32_e32 v66, 0x3fb8aa3b, v66
	v_add_f32_e32 v80, v81, v80
	v_add_f32_e32 v81, v154, v155
	v_exp_f32_e32 v180, v82
	v_sub_f32_e32 v82, v95, v182
	v_exp_f32_e32 v193, v66
	v_sub_f32_e32 v66, v75, v182
	v_add_f32_e32 v80, v81, v80
	v_add_f32_e32 v81, v156, v157
	v_mul_f32_e32 v82, 0x3fb8aa3b, v82
	v_mul_f32_e32 v64, 0x3fb8aa3b, v64
	v_mul_f32_e32 v66, 0x3fb8aa3b, v66
	v_add_f32_e32 v80, v81, v80
	v_add_f32_e32 v81, v158, v159
	v_exp_f32_e32 v181, v82
	v_exp_f32_e32 v185, v64
	v_sub_f32_e32 v64, v67, v182
	v_exp_f32_e32 v194, v66
	v_sub_f32_e32 v66, v76, v182
	v_add_f32_e32 v80, v81, v80
	v_add_f32_e32 v81, v174, v175
	v_mul_f32_e32 v64, 0x3fb8aa3b, v64
	v_mul_f32_e32 v66, 0x3fb8aa3b, v66
	v_add_f32_e32 v80, v81, v80
	v_add_f32_e32 v81, v176, v177
	v_exp_f32_e32 v186, v64
	v_exp_f32_e32 v195, v66
	v_sub_f32_e32 v66, v77, v182
	v_add_f32_e32 v80, v81, v80
	v_add_f32_e32 v81, v178, v179
	v_mul_f32_e32 v66, 0x3fb8aa3b, v66
	v_add_f32_e32 v80, v81, v80
	v_add_f32_e32 v81, v180, v181
	v_exp_f32_e32 v196, v66
	v_sub_f32_e32 v66, v78, v182
	v_add_f32_e32 v64, v81, v80
	v_add_f32_e32 v65, v183, v184
	v_mul_f32_e32 v66, 0x3fb8aa3b, v66
	v_add_f32_e32 v64, v65, v64
	v_add_f32_e32 v65, v185, v186
	v_exp_f32_e32 v197, v66
	v_sub_f32_e32 v66, v79, v182
	v_add_f32_e32 v64, v65, v64
	v_add_f32_e32 v65, v187, v188
	v_mul_f32_e32 v66, 0x3fb8aa3b, v66
	v_add_f32_e32 v64, v65, v64
	v_add_f32_e32 v65, v189, v190
	v_exp_f32_e32 v198, v66
	v_add_f32_e32 v64, v65, v64
	v_add_f32_e32 v65, v191, v192
	v_add_f32_e32 v64, v65, v64
	v_add_f32_e32 v65, v193, v194
	v_add_f32_e32 v64, v65, v64
	v_add_f32_e32 v65, v195, v196
	v_add_f32_e32 v64, v65, v64
	v_add_f32_e32 v65, v197, v198
	v_add_f32_e32 v182, v65, v64
	ds_bpermute_b32 v137, v137, v182
	s_waitcnt lgkmcnt(0)
	s_barrier
	v_lshrrev_b32_e32 v108, 5, v133
	v_add_u32_e32 v68, s7, v108
	v_ashrrev_i32_e32 v69, 31, v68
	v_lshlrev_b64 v[68:69], 12, v[68:69]
	v_lshl_add_u64 v[68:69], v[128:129], 0, v[68:69]
	v_mad_u32_u24 v70, v108, s54, v132
	s_mov_b64 s[34:35], 0x10000
	v_add_u32_e32 v71, 0x12000, v70
	global_load_dwordx4 v[64:67], v[68:69], off offset:2048
	v_lshl_add_u64 v[68:69], v[68:69], 0, s[34:35]
	global_load_dwordx4 v[72:75], v[68:69], off offset:2048
	v_lshl_add_u64 v[68:69], v[68:69], 0, s[34:35]
	global_load_dwordx4 v[76:79], v[68:69], off offset:2048
	v_lshl_add_u64 v[68:69], v[68:69], 0, s[34:35]
	global_load_dwordx4 v[80:83], v[68:69], off offset:2048
	v_lshl_add_u64 v[68:69], v[68:69], 0, s[34:35]
	global_load_dwordx4 v[84:87], v[68:69], off offset:2048
	v_lshl_add_u64 v[68:69], v[68:69], 0, s[34:35]
	global_load_dwordx4 v[88:91], v[68:69], off offset:2048
	v_lshl_add_u64 v[68:69], v[68:69], 0, s[34:35]
	global_load_dwordx4 v[92:95], v[68:69], off offset:2048
	v_lshl_add_u64 v[68:69], v[68:69], 0, s[34:35]
	global_load_dwordx4 v[96:99], v[68:69], off offset:2048
	v_lshl_add_u64 v[68:69], v[68:69], 0, s[34:35]
	global_load_dwordx4 v[100:103], v[68:69], off offset:2048
	v_lshl_add_u64 v[68:69], v[68:69], 0, s[34:35]
	global_load_dwordx4 v[104:107], v[68:69], off offset:2048
	v_lshl_add_u64 v[68:69], v[68:69], 0, s[34:35]
	global_load_dwordx4 v[200:203], v[68:69], off offset:2048
	v_lshl_add_u64 v[68:69], v[68:69], 0, s[34:35]
	global_load_dwordx4 v[204:207], v[68:69], off offset:2048
	v_lshl_add_u64 v[68:69], v[68:69], 0, s[34:35]
	global_load_dwordx4 v[208:211], v[68:69], off offset:2048
	v_lshl_add_u64 v[68:69], v[68:69], 0, s[34:35]
	global_load_dwordx4 v[232:235], v[68:69], off offset:2048
	v_lshl_add_u64 v[68:69], v[68:69], 0, s[34:35]
	global_load_dwordx4 v[236:239], v[68:69], off offset:2048
	v_lshl_add_u64 v[68:69], v[68:69], 0, s[34:35]
	global_load_dwordx4 v[240:243], v[68:69], off offset:2048
	s_waitcnt vmcnt(15)
	ds_write_b128 v70, v[64:67]
	s_waitcnt vmcnt(14)
	ds_write_b128 v70, v[72:75] offset:9216
	s_waitcnt vmcnt(13)
	ds_write_b128 v70, v[76:79] offset:18432
	s_waitcnt vmcnt(12)
	ds_write_b128 v70, v[80:83] offset:27648
	s_waitcnt vmcnt(11)
	ds_write_b128 v70, v[84:87] offset:36864
	s_waitcnt vmcnt(10)
	ds_write_b128 v70, v[88:91] offset:46080
	s_waitcnt vmcnt(9)
	ds_write_b128 v70, v[92:95] offset:55296
	s_waitcnt vmcnt(8)
	ds_write_b128 v70, v[96:99] offset:64512
	s_waitcnt vmcnt(7)
	ds_write_b128 v71, v[100:103]
	s_waitcnt vmcnt(6)
	ds_write_b128 v71, v[104:107] offset:9216
	s_waitcnt vmcnt(5)
	ds_write_b128 v71, v[200:203] offset:18432
	s_waitcnt vmcnt(4)
	ds_write_b128 v71, v[204:207] offset:27648
	s_waitcnt vmcnt(3)
	ds_write_b128 v71, v[208:211] offset:36864
	s_waitcnt vmcnt(2)
	ds_write_b128 v71, v[232:235] offset:46080
	s_waitcnt vmcnt(1)
	ds_write_b128 v71, v[236:239] offset:55296
	s_waitcnt vmcnt(0)
; __device__ __forceinline__ unsigned cvt_pk_bf16(float lo, float hi) { f32x2 v = {lo, hi}; bf16x2_t b = __builtin_convertvector(v, bf16x2_t); return __builtin_bit_cast(unsigned, b); }
; __device__ __forceinline__ float bf_lo(unsigned u) { return __uint_as_float(u << 16); }
; __device__ __forceinline__ float bf_hi(unsigned u) { return __uint_as_float(u & 0xffff0000u); }
; __device__ __forceinline__ bf16x8 scale_frag(bf16x8 q, float s) {
;   u32x4 u = (u32x4)q; u32x4 o;
; #pragma unroll
;   for (int i = 0; i < 4; ++i) o[i] = cvt_pk_bf16(bf_lo(u[i]) * s, bf_hi(u[i]) * s);
;   return (bf16x8)o;
; }
; __device__ void attn_item(const bf16_t* __restrict__ QX, const bf16_t* __restrict__ KV, bf16_t* __restrict__ O, int tt, int head, LAS unsigned char* lds) {
;     ...
;     if (hf == 1) { const float f = __builtin_amdgcn_exp2f((mxp - mx) * 1.4426950408889634f); sum *= f;
; #pragma unroll
;       for (int mt = 0; mt < 4; ++mt) { pf[mt][0] = scale_frag(pf[mt][0], f); pf[mt][1] = scale_frag(pf[mt][1], f); } }
	ds_write_b128 v71, v[240:243] offset:64512
	s_movk_i32 s12, 0x2000
	v_cvt_pk_bf16_f32 v48, v48, v49
	v_cvt_pk_bf16_f32 v32, v32, v33
	v_cvt_pk_bf16_f32 v33, v34, v35
	v_cvt_pk_bf16_f32 v34, v36, v37
	v_cvt_pk_bf16_f32 v36, v40, v41
	v_cvt_pk_bf16_f32 v40, v16, v17
	v_lshlrev_b32_e32 v16, 16, v48
	v_and_b32_e32 v17, 0xffff0000, v48
	v_cvt_pk_bf16_f32 v49, v50, v51
	v_pk_mul_f32 v[16:17], v[0:1], v[16:17] op_sel_hi:[0,1]
	v_cvt_pk_bf16_f32 v64, v16, v17
	v_lshlrev_b32_e32 v16, 16, v49
	v_and_b32_e32 v17, 0xffff0000, v49
	v_cvt_pk_bf16_f32 v50, v52, v53
	v_pk_mul_f32 v[16:17], v[0:1], v[16:17] op_sel_hi:[0,1]
	v_cvt_pk_bf16_f32 v65, v16, v17
	v_lshlrev_b32_e32 v16, 16, v50
	v_and_b32_e32 v17, 0xffff0000, v50
	v_cvt_pk_bf16_f32 v51, v54, v55
	v_pk_mul_f32 v[16:17], v[0:1], v[16:17] op_sel_hi:[0,1]
	v_cvt_pk_bf16_f32 v66, v16, v17
	v_lshlrev_b32_e32 v16, 16, v51
	v_and_b32_e32 v17, 0xffff0000, v51
	v_cvt_pk_bf16_f32 v52, v56, v57
	v_pk_mul_f32 v[16:17], v[0:1], v[16:17] op_sel_hi:[0,1]
	v_cvt_pk_bf16_f32 v67, v16, v17
	v_lshlrev_b32_e32 v16, 16, v52
	v_and_b32_e32 v17, 0xffff0000, v52
	v_cvt_pk_bf16_f32 v53, v58, v59
	v_pk_mul_f32 v[16:17], v[0:1], v[16:17] op_sel_hi:[0,1]
	v_cvt_pk_bf16_f32 v68, v16, v17
	v_lshlrev_b32_e32 v16, 16, v53
	v_and_b32_e32 v17, 0xffff0000, v53
	v_cvt_pk_bf16_f32 v54, v60, v61
	v_pk_mul_f32 v[16:17], v[0:1], v[16:17] op_sel_hi:[0,1]
	v_cvt_pk_bf16_f32 v69, v16, v17
	v_lshlrev_b32_e32 v16, 16, v54
	v_and_b32_e32 v17, 0xffff0000, v54
	v_cvt_pk_bf16_f32 v55, v62, v63
	v_pk_mul_f32 v[16:17], v[0:1], v[16:17] op_sel_hi:[0,1]
	v_cvt_pk_bf16_f32 v70, v16, v17
	v_lshlrev_b32_e32 v16, 16, v55
	v_and_b32_e32 v17, 0xffff0000, v55
	v_pk_mul_f32 v[16:17], v[0:1], v[16:17] op_sel_hi:[0,1]
	v_cvt_pk_bf16_f32 v71, v16, v17
	v_lshlrev_b32_e32 v16, 16, v32
	v_and_b32_e32 v17, 0xffff0000, v32
	v_pk_mul_f32 v[16:17], v[0:1], v[16:17] op_sel_hi:[0,1]
	v_cvt_pk_bf16_f32 v72, v16, v17
	v_lshlrev_b32_e32 v16, 16, v33
	v_and_b32_e32 v17, 0xffff0000, v33
	v_pk_mul_f32 v[16:17], v[0:1], v[16:17] op_sel_hi:[0,1]
	v_cvt_pk_bf16_f32 v73, v16, v17
	v_lshlrev_b32_e32 v16, 16, v34
	v_and_b32_e32 v17, 0xffff0000, v34
	v_cvt_pk_bf16_f32 v35, v38, v39
	v_pk_mul_f32 v[16:17], v[0:1], v[16:17] op_sel_hi:[0,1]
	v_cvt_pk_bf16_f32 v74, v16, v17
	v_lshlrev_b32_e32 v16, 16, v35
	v_and_b32_e32 v17, 0xffff0000, v35
	v_pk_mul_f32 v[16:17], v[0:1], v[16:17] op_sel_hi:[0,1]
	v_cvt_pk_bf16_f32 v75, v16, v17
	v_lshlrev_b32_e32 v16, 16, v36
	v_and_b32_e32 v17, 0xffff0000, v36
	v_cvt_pk_bf16_f32 v37, v42, v43
	v_pk_mul_f32 v[16:17], v[0:1], v[16:17] op_sel_hi:[0,1]
	v_cvt_pk_bf16_f32 v76, v16, v17
	v_lshlrev_b32_e32 v16, 16, v37
	v_and_b32_e32 v17, 0xffff0000, v37
	v_cvt_pk_bf16_f32 v38, v44, v45
	v_pk_mul_f32 v[16:17], v[0:1], v[16:17] op_sel_hi:[0,1]
	v_cvt_pk_bf16_f32 v77, v16, v17
	v_lshlrev_b32_e32 v16, 16, v38
	v_and_b32_e32 v17, 0xffff0000, v38
	v_cvt_pk_bf16_f32 v39, v46, v47
	v_pk_mul_f32 v[16:17], v[0:1], v[16:17] op_sel_hi:[0,1]
	v_cvt_pk_bf16_f32 v78, v16, v17
	v_lshlrev_b32_e32 v16, 16, v39
	v_and_b32_e32 v17, 0xffff0000, v39
	v_pk_mul_f32 v[16:17], v[0:1], v[16:17] op_sel_hi:[0,1]
	v_cvt_pk_bf16_f32 v79, v16, v17
	v_lshlrev_b32_e32 v16, 16, v40
	v_and_b32_e32 v17, 0xffff0000, v40
	v_cvt_pk_bf16_f32 v18, v18, v19
	v_pk_mul_f32 v[16:17], v[0:1], v[16:17] op_sel_hi:[0,1]
	v_cvt_pk_bf16_f32 v80, v16, v17
	v_lshlrev_b32_e32 v16, 16, v18
	v_and_b32_e32 v17, 0xffff0000, v18
	v_cvt_pk_bf16_f32 v19, v20, v21
	v_pk_mul_f32 v[16:17], v[0:1], v[16:17] op_sel_hi:[0,1]
	v_cvt_pk_bf16_f32 v81, v16, v17
	v_lshlrev_b32_e32 v16, 16, v19
	v_and_b32_e32 v17, 0xffff0000, v19
	v_cvt_pk_bf16_f32 v20, v22, v23
	v_pk_mul_f32 v[16:17], v[0:1], v[16:17] op_sel_hi:[0,1]
	v_cvt_pk_bf16_f32 v82, v16, v17
	v_lshlrev_b32_e32 v16, 16, v20
	v_and_b32_e32 v17, 0xffff0000, v20
	v_cvt_pk_bf16_f32 v21, v24, v25
	v_pk_mul_f32 v[16:17], v[0:1], v[16:17] op_sel_hi:[0,1]
	v_cvt_pk_bf16_f32 v83, v16, v17
	v_lshlrev_b32_e32 v16, 16, v21
	v_and_b32_e32 v17, 0xffff0000, v21
	v_cvt_pk_bf16_f32 v22, v26, v27
	v_pk_mul_f32 v[16:17], v[0:1], v[16:17] op_sel_hi:[0,1]
	v_cvt_pk_bf16_f32 v84, v16, v17
	v_lshlrev_b32_e32 v16, 16, v22
	v_and_b32_e32 v17, 0xffff0000, v22
	v_cvt_pk_bf16_f32 v23, v28, v29
; __device__ __forceinline__ unsigned cvt_pk_bf16(float lo, float hi) { f32x2 v = {lo, hi}; bf16x2_t b = __builtin_convertvector(v, bf16x2_t); return __builtin_bit_cast(unsigned, b); }
; __device__ void attn_item(const bf16_t* __restrict__ QX, const bf16_t* __restrict__ KV, bf16_t* __restrict__ O, int tt, int head, LAS unsigned char* lds) {
;     ...
;     if (hf == 1) { const float f = __builtin_amdgcn_exp2f((mxp - mx) * 1.4426950408889634f); sum *= f;
; #pragma unroll
;       for (int mt = 0; mt < 4; ++mt) { pf[mt][0] = scale_frag(pf[mt][0], f); pf[mt][1] = scale_frag(pf[mt][1], f); } }
; #pragma unroll
;     for (int mt = 0; mt < 4; ++mt) {
;       u32x4 p0, p1;
; #pragma unroll
;       for (int r = 0; r < 16; r += 2) {
;         const float e0 = __builtin_amdgcn_exp2f((sc[mt][r] - mx) * 1.4426950408889634f), e1 = __builtin_amdgcn_exp2f((sc[mt][r + 1] - mx) * 1.4426950408889634f);
;         sum += e0 + e1; const unsigned pk = cvt_pk_bf16(e0, e1);
;         if (r < 8) p0[r >> 1] = pk; else p1[(r - 8) >> 1] = pk;
;       }
;       pf[hf * 4 + mt][0] = (bf16x8)p0; pf[hf * 4 + mt][1] = (bf16x8)p1;
;     }
;     mxp = mx;
;   }
;   sum += __shfl_xor(sum, 32);
;   const float inv = __builtin_amdgcn_rcpf(sum);
;     ...
;     const unsigned cofs = (unsigned)(half * 128 + 16 * G1 + 4 * p4) * 2u;
; #pragma unroll
;     for (int mt = 0; mt < 8; ++mt)
; #pragma unroll
;       for (int s = 0; s < 2; ++s) {
;         const unsigned r = (unsigned)(mt * 32 + 16 * s + 4 * h + q4);
	v_pk_mul_f32 v[16:17], v[0:1], v[16:17] op_sel_hi:[0,1]
	v_cvt_pk_bf16_f32 v85, v16, v17
	v_lshlrev_b32_e32 v16, 16, v23
	v_and_b32_e32 v17, 0xffff0000, v23
	v_cvt_pk_bf16_f32 v24, v30, v31
	v_pk_mul_f32 v[16:17], v[0:1], v[16:17] op_sel_hi:[0,1]
	v_cvt_pk_bf16_f32 v86, v16, v17
	v_lshlrev_b32_e32 v16, 16, v24
	v_and_b32_e32 v17, 0xffff0000, v24
	v_cvt_pk_bf16_f32 v25, v134, v135
	v_pk_mul_f32 v[16:17], v[0:1], v[16:17] op_sel_hi:[0,1]
	v_cvt_pk_bf16_f32 v87, v16, v17
	v_lshlrev_b32_e32 v16, 16, v25
	v_and_b32_e32 v17, 0xffff0000, v25
	v_cvt_pk_bf16_f32 v26, v138, v139
	v_pk_mul_f32 v[16:17], v[0:1], v[16:17] op_sel_hi:[0,1]
	v_cvt_pk_bf16_f32 v88, v16, v17
	v_lshlrev_b32_e32 v16, 16, v26
	v_and_b32_e32 v17, 0xffff0000, v26
	v_cvt_pk_bf16_f32 v27, v140, v141
	v_pk_mul_f32 v[16:17], v[0:1], v[16:17] op_sel_hi:[0,1]
	v_cvt_pk_bf16_f32 v89, v16, v17
	v_lshlrev_b32_e32 v16, 16, v27
	v_and_b32_e32 v17, 0xffff0000, v27
	v_cvt_pk_bf16_f32 v28, v142, v143
	v_pk_mul_f32 v[16:17], v[0:1], v[16:17] op_sel_hi:[0,1]
	v_cvt_pk_bf16_f32 v90, v16, v17
	v_lshlrev_b32_e32 v16, 16, v28
	v_and_b32_e32 v17, 0xffff0000, v28
	v_cvt_pk_bf16_f32 v29, v144, v145
	v_pk_mul_f32 v[16:17], v[0:1], v[16:17] op_sel_hi:[0,1]
	v_cvt_pk_bf16_f32 v91, v16, v17
	v_lshlrev_b32_e32 v16, 16, v29
	v_and_b32_e32 v17, 0xffff0000, v29
	v_cvt_pk_bf16_f32 v30, v146, v147
	v_pk_mul_f32 v[16:17], v[0:1], v[16:17] op_sel_hi:[0,1]
	v_cvt_pk_bf16_f32 v92, v16, v17
	v_lshlrev_b32_e32 v16, 16, v30
	v_and_b32_e32 v17, 0xffff0000, v30
	v_cvt_pk_bf16_f32 v31, v148, v149
	v_pk_mul_f32 v[16:17], v[0:1], v[16:17] op_sel_hi:[0,1]
	v_cvt_pk_bf16_f32 v93, v16, v17
	v_lshlrev_b32_e32 v16, 16, v31
	v_and_b32_e32 v17, 0xffff0000, v31
	v_cvt_pk_bf16_f32 v41, v150, v151
	v_pk_mul_f32 v[16:17], v[0:1], v[16:17] op_sel_hi:[0,1]
	v_cvt_pk_bf16_f32 v94, v16, v17
	v_lshlrev_b32_e32 v16, 16, v41
	v_and_b32_e32 v17, 0xffff0000, v41
	v_pk_mul_f32 v[16:17], v[0:1], v[16:17] op_sel_hi:[0,1]
	v_cvt_pk_bf16_f32 v96, v1, v2
	v_add_f32_e32 v1, v182, v137
	v_rcp_f32_e32 v128, v1
	v_cvt_pk_bf16_f32 v95, v16, v17
	v_cvt_pk_bf16_f32 v97, v3, v4
	v_cvt_pk_bf16_f32 v98, v5, v6
	v_cvt_pk_bf16_f32 v99, v7, v8
	v_cvt_pk_bf16_f32 v100, v9, v10
	v_cvt_pk_bf16_f32 v101, v11, v12
	v_cvt_pk_bf16_f32 v102, v13, v14
	v_cvt_pk_bf16_f32 v103, v15, v112
	v_cvt_pk_bf16_f32 v104, v113, v114
	v_cvt_pk_bf16_f32 v105, v115, v116
	v_cvt_pk_bf16_f32 v106, v117, v118
	v_cvt_pk_bf16_f32 v107, v119, v120
	v_cvt_pk_bf16_f32 v108, v121, v122
	v_cvt_pk_bf16_f32 v109, v123, v124
	v_cvt_pk_bf16_f32 v110, v125, v126
	v_cvt_pk_bf16_f32 v111, v127, v111
	v_cvt_pk_bf16_f32 v112, v152, v153
	v_cvt_pk_bf16_f32 v113, v154, v155
	v_cvt_pk_bf16_f32 v114, v156, v157
	v_cvt_pk_bf16_f32 v115, v158, v159
	v_cvt_pk_bf16_f32 v116, v174, v175
	v_cvt_pk_bf16_f32 v117, v176, v177
	v_cvt_pk_bf16_f32 v118, v178, v179
	v_cvt_pk_bf16_f32 v119, v180, v181
	v_cvt_pk_bf16_f32 v120, v183, v184
	v_cvt_pk_bf16_f32 v121, v185, v186
	v_cvt_pk_bf16_f32 v122, v187, v188
	v_cvt_pk_bf16_f32 v123, v189, v190
	v_cvt_pk_bf16_f32 v124, v191, v192
	v_cvt_pk_bf16_f32 v125, v193, v194
	v_cvt_pk_bf16_f32 v126, v195, v196
	v_cvt_pk_bf16_f32 v127, v197, v198
	v_bfe_u32 v0, v133, 2, 2
	v_and_b32_e32 v2, 16, v133
	s_waitcnt lgkmcnt(0)
	s_barrier
	v_lshlrev_b32_e32 v1, 2, v133
	v_and_or_b32 v132, v1, 12, v2
	v_lshl_or_b32 v2, v136, 2, v0
	v_lshlrev_b64 v[0:1], 11, v[130:131]
	v_lshl_add_u64 v[0:1], s[10:11], 0, v[0:1]
	v_lshl_add_u64 v[0:1], s[22:23], 1, v[0:1]
	v_lshl_add_u64 v[130:131], v[0:1], 0, v[160:161]
	v_mov_b32_e32 v0, 0x14400
	v_mul_u32_u24_e32 v133, 0x240, v2
	v_mad_u32_u24 v138, v2, s54, v0
	v_mov_b32_e32 v0, 0x16800
	v_mad_u32_u24 v134, v2, s54, 0
	v_or_b32_e32 v136, 0x12000, v133
	v_mad_u32_u24 v140, v2, s54, v0
	v_mad_u32_u24 v142, v2, s54, v221
	v_or_b32_e32 v144, 0x1b000, v133
	v_mad_u32_u24 v146, v2, s54, v218
	v_mad_u32_u24 v148, v2, s54, v216
	v_mad_u32_u24 v150, v2, s54, v224
	v_add_u32_e32 v135, 0xfc00, v134
	v_add_u32_e32 v137, 0, v136
	v_add_u32_e32 v139, 0, v138
	v_add_u32_e32 v141, 0, v140
	v_add_u32_e32 v143, 0, v142
	v_add_u32_e32 v145, 0, v144
	v_add_u32_e32 v147, 0, v146
	v_add_u32_e32 v149, 0, v148
	v_add_u32_e32 v151, 0, v150
	v_mov_b32_e32 v129, v128
	s_mov_b32 s20, 0
	s_mov_b64 s[22:23], -1
